# saddr+voffset form for the up G stores and the Wo out/xg stores (one address dword per lane)
# speedup vs baseline: 1.0009x; 1.0009x over previous
;     __device__ __forceinline__ void operator()(const f32x4 (&acc)[2][2][4][2], const Unit& u, int wr, int wc, int fr, int fq) const {
;         const int row0 = u.pm * BM + wr * 64 + fr, col0 = u.pn * BM + wc * 32 + 4 * fq;
;         const float* base = (u.pm * BM < TOKP) ? base_p : base_s;
;         const int b = batch_of(u.pm * BM);
;         const float* gp = gate + (size_t)b * (6 * DM) + col0;
;         f32x4 gv[2][2], gg[2][2], gs[2][2];
; #pragma unroll
;         for (int bj = 0; bj < 2; ++bj)
; #pragma unroll
;             for (int n = 0; n < 2; ++n) { gv[bj][n] = LDG(f32x4, gp + bj * HALF + n * 16);
;                 if (NEXT) { gg[bj][n] = LDG(f32x4, gain + col0 + bj * HALF + n * 16); gs[bj][n] = LDG(f32x4, scale + (size_t)b * (6 * DM) + col0 + bj * HALF + n * 16); } }
;         f32x4 bs0[2][2][2];
; #pragma unroll
;         for (int mm = 0; mm < 2; ++mm)
; #pragma unroll
;             for (int bj = 0; bj < 2; ++bj)
; #pragma unroll
;                 for (int n = 0; n < 2; ++n) { const size_t o_ = (size_t)(row0 + mm * 16) * DM + col0 + bj * HALF + n * 16;
;                     if (RES_BF16) { const u32x2 r = LDG(u32x2, xres + o_); bs0[mm][bj][n] = (f32x4){bf_lo(r.x), bf_hi(r.x), bf_lo(r.y), bf_hi(r.y)}; }
;                     else bs0[mm][bj][n] = LDG(f32x4, base + o_); }
;         asm volatile("" ::: "memory");
;         if (NEXT) {
; #pragma unroll
;             for (int bj = 0; bj < 2; ++bj)
; #pragma unroll
;                 for (int n = 0; n < 2; ++n) gg[bj][n] = gg[bj][n] * (gs[bj][n] + 1.0f); }
; #pragma unroll
;         for (int ai = 0; ai < 2; ++ai)
; #pragma unroll
;         for (int mp = 0; mp < 2; ++mp) {
;             f32x4 bs[2][2][2];
; #pragma unroll
;             for (int mm = 0; mm < 2; ++mm)
; #pragma unroll
;                 for (int bj = 0; bj < 2; ++bj)
; #pragma unroll
;                     for (int n = 0; n < 2; ++n) { const size_t o_ = (size_t)(row0 + ai * HALF + (2 * mp + mm) * 16) * DM + col0 + bj * HALF + n * 16;
;                         if (ai == 0 && mp == 0) bs[mm][bj][n] = bs0[mm][bj][n];
;                         else if (RES_BF16) { const u32x2 r = LDG(u32x2, xres + o_); bs[mm][bj][n] = (f32x4){bf_lo(r.x), bf_hi(r.x), bf_lo(r.y), bf_hi(r.y)}; }
;                         else bs[mm][bj][n] = LDG(f32x4, base + o_); }
;             asm volatile("" ::: "memory");
; #pragma unroll
.LBB0_1202:
	s_lshl_b32 s29, s27, 8
	s_add_i32 s4, s29, 0xffffe000
	s_lshr_b32 s4, s4, 12
	s_ashr_i32 s6, s27, 3
	s_add_i32 s7, s4, 4
	s_cmp_lt_i32 s27, 32
	s_cselect_b32 s6, s6, s7
	v_lshl_or_b32 v180, s28, 8, v206
	s_mul_i32 s28, s6, 0xc000
	s_cselect_b32 s5, s45, s49
	s_cselect_b32 s4, s44, s48
	s_mul_hi_i32 s27, s6, 0xc000
	s_add_u32 s6, s79, s28
	v_ashrrev_i32_e32 v181, 31, v180
	s_addc_u32 s7, s83, s27
	v_lshlrev_b64 v[146:147], 2, v[180:181]
	v_lshl_add_u64 v[50:51], s[6:7], 0, v[146:147]
	s_add_u32 s6, s85, s28
	s_addc_u32 s7, s87, s27
	v_lshl_add_u64 v[148:149], s[52:53], 0, v[146:147]
	v_lshl_add_u64 v[150:151], s[6:7], 0, v[146:147]
	global_load_dwordx4 v[62:65], v[50:51], off
	global_load_dwordx4 v[182:185], v[148:149], off
	global_load_dwordx4 v[186:189], v[150:151], off
	global_load_dwordx4 v[58:61], v[50:51], off offset:64
	global_load_dwordx4 v[208:211], v[148:149], off offset:64
	global_load_dwordx4 v[190:193], v[150:151], off offset:64
	global_load_dwordx4 v[54:57], v[50:51], off offset:512
	global_load_dwordx4 v[212:215], v[148:149], off offset:512
	global_load_dwordx4 v[216:219], v[150:151], off offset:512
	s_nop 0
	global_load_dwordx4 v[50:53], v[50:51], off offset:576
	s_nop 0
	global_load_dwordx4 v[220:223], v[148:149], off offset:576
	global_load_dwordx4 v[240:243], v[150:151], off offset:576
	v_add_u32_e32 v200, s29, v204
	v_ashrrev_i32_e32 v201, 31, v200
	v_lshl_add_u64 v[198:199], s[4:5], 0, v[146:147]
	v_lshlrev_b64 v[146:147], 13, v[200:201]
	v_lshl_add_u64 v[146:147], v[198:199], 0, v[146:147]
	global_load_dwordx4 v[244:247], v[146:147], off
	global_load_dwordx4 v[170:173], v[146:147], off offset:64
	global_load_dwordx4 v[166:169], v[146:147], off offset:512
	global_load_dwordx4 v[162:165], v[146:147], off offset:576
	v_or_b32_e32 v202, 16, v200
	v_ashrrev_i32_e32 v203, 31, v202
	v_lshlrev_b64 v[146:147], 13, v[202:203]
	v_lshl_add_u64 v[146:147], v[198:199], 0, v[146:147]
	global_load_dwordx4 v[158:161], v[146:147], off
	global_load_dwordx4 v[154:157], v[146:147], off offset:64
	global_load_dwordx4 v[150:153], v[146:147], off offset:512
	s_nop 0
	global_load_dwordx4 v[146:149], v[146:147], off offset:576
	s_waitcnt vmcnt(0)
	v_pk_add_f32 v[186:187], v[186:187], 1.0 op_sel_hi:[1,0]
	v_pk_add_f32 v[188:189], v[188:189], 1.0 op_sel_hi:[1,0]
	v_pk_mul_f32 v[196:197], v[182:183], v[186:187]
	v_pk_add_f32 v[182:183], v[192:193], 1.0 op_sel_hi:[1,0]
	v_pk_mul_f32 v[194:195], v[184:185], v[188:189]
	v_pk_add_f32 v[184:185], v[190:191], 1.0 op_sel_hi:[1,0]
	v_pk_mul_f32 v[190:191], v[210:211], v[182:183]
	v_pk_add_f32 v[182:183], v[218:219], 1.0 op_sel_hi:[1,0]
	v_pk_mul_f32 v[192:193], v[208:209], v[184:185]
	v_pk_add_f32 v[184:185], v[216:217], 1.0 op_sel_hi:[1,0]
	v_pk_mul_f32 v[186:187], v[214:215], v[182:183]
	v_pk_add_f32 v[182:183], v[242:243], 1.0 op_sel_hi:[1,0]
	v_pk_add_f32 v[208:209], v[240:241], 1.0 op_sel_hi:[1,0]
	v_pk_mul_f32 v[188:189], v[212:213], v[184:185]
	v_pk_mul_f32 v[184:185], v[222:223], v[182:183]
	v_pk_mul_f32 v[182:183], v[220:221], v[208:209]
	v_lshlrev_b64 v[208:209], 11, v[200:201]
	v_lshl_add_u64 v[212:213], v[208:209], 0, v[180:181]
	v_pk_fma_f32 v[210:211], v[144:145], v[64:65], v[246:247]
	v_pk_fma_f32 v[208:209], v[142:143], v[62:63], v[244:245]
	v_mul_f32_e32 v145, v211, v211
	v_mul_f32_e32 v144, v209, v209
	v_lshlrev_b32_e32 v142, 2, v212
	v_fmac_f32_e32 v144, v208, v208
	v_fmac_f32_e32 v145, v210, v210
	global_store_dwordx4 v142, v[208:211], s[40:41]
	v_add_f32_e32 v214, v144, v145
	v_pk_mul_f32 v[144:145], v[194:195], v[210:211]
	v_pk_mul_f32 v[208:209], v[196:197], v[208:209]
	v_pk_fma_f32 v[138:139], v[138:139], v[58:59], v[170:171]
	v_cvt_pk_bf16_f32 v248, v208, v209
	v_cvt_pk_bf16_f32 v249, v144, v145
	v_lshlrev_b32_e32 v144, 1, v212
	v_pk_fma_f32 v[140:141], v[140:141], v[60:61], v[172:173]
	v_mul_f32_e32 v170, v139, v139
	global_store_dwordx4 v142, v[138:141], s[40:41] offset:64
	v_fmac_f32_e32 v170, v138, v138
	v_mul_f32_e32 v171, v141, v141
	v_pk_mul_f32 v[138:139], v[192:193], v[138:139]
	v_pk_fma_f32 v[134:135], v[134:135], v[54:55], v[166:167]
	v_cvt_pk_bf16_f32 v250, v138, v139
	v_fmac_f32_e32 v171, v140, v140
	v_pk_mul_f32 v[140:141], v[190:191], v[140:141]
	v_pk_fma_f32 v[136:137], v[136:137], v[56:57], v[168:169]
	v_cvt_pk_bf16_f32 v251, v140, v141
	v_add_u32_e32 v252, v236, v144
	s_nop 0
	v_permlane16_swap_b32_e32 v248, v250
	v_permlane16_swap_b32_e32 v249, v251
	global_store_dwordx4 v252, v[248:251], s[42:43]
	s_nop 1
	v_mul_f32_e32 v138, v135, v135
	global_store_dwordx4 v142, v[134:137], s[40:41] offset:512
	v_fmac_f32_e32 v138, v134, v134
	v_mul_f32_e32 v139, v137, v137
	v_pk_mul_f32 v[134:135], v[188:189], v[134:135]
	v_fmac_f32_e32 v139, v136, v136
	v_pk_mul_f32 v[136:137], v[186:187], v[136:137]
	v_cvt_pk_bf16_f32 v248, v134, v135
	v_pk_fma_f32 v[132:133], v[132:133], v[52:53], v[164:165]
	v_cvt_pk_bf16_f32 v249, v136, v137
	v_pk_fma_f32 v[130:131], v[130:131], v[50:51], v[162:163]
	v_add_f32_e32 v170, v170, v171
	v_mul_f32_e32 v134, v131, v131
	v_mul_f32_e32 v135, v133, v133
	v_add_f32_e32 v170, v214, v170
	v_add_f32_e32 v138, v138, v139
	v_fmac_f32_e32 v134, v130, v130
	v_fmac_f32_e32 v135, v132, v132
	v_add_f32_e32 v138, v170, v138
	global_store_dwordx4 v142, v[130:133], s[40:41] offset:576
	v_add_f32_e32 v134, v134, v135
	v_add_f32_e32 v134, v138, v134
	v_pk_mul_f32 v[130:131], v[182:183], v[130:131]
	v_pk_mul_f32 v[132:133], v[184:185], v[132:133]
	v_cvt_pk_bf16_f32 v250, v130, v131
	s_nop 0
	v_cvt_pk_bf16_f32 v251, v132, v133
	v_add_u32_e32 v252, v236, v144
	s_nop 0
	v_permlane16_swap_b32_e32 v248, v250
	v_permlane16_swap_b32_e32 v249, v251
	global_store_dwordx4 v252, v[248:251], s[42:43] offset:256
	s_nop 1
	ds_swizzle_b32 v130, v134 offset:swizzle(SWAP,16)
	s_waitcnt lgkmcnt(0)
	v_add_f32_e32 v130, v134, v130
	v_mov_b32_e32 v131, v130
	s_nop 1
	v_permlane32_swap_b32_e32 v130, v131
	v_lshl_add_u64 v[134:135], v[200:201], 2, s[54:55]
	s_and_saveexec_b64 s[4:5], s[36:37]
	s_cbranch_execz .LBB0_1204
	v_add_f32_e32 v130, v130, v131
	global_atomic_add_f32 v[134:135], v130, off
; __device__ __forceinline__ unsigned cvt_pk_bf16(float lo, float hi) { unsigned r; asm volatile("v_cvt_pk_bf16_f32 %0, %1, %2" : "=v"(r) : "v"(lo), "v"(hi)); return r; }
; __device__ __forceinline__ float bf_lo(unsigned w) { return __uint_as_float(w << 16); }
;     __device__ __forceinline__ void operator()(const f32x4 (&acc)[2][2][4][2], const Unit& u, int wr, int wc, int fr, int fq) const {
;     ...
;         for (int mp = 0; mp < 2; ++mp) {
;             f32x4 bs[2][2][2];
; #pragma unroll
;             for (int mm = 0; mm < 2; ++mm)
; #pragma unroll
;                 for (int bj = 0; bj < 2; ++bj)
; #pragma unroll
;                     for (int n = 0; n < 2; ++n) { const size_t o_ = (size_t)(row0 + ai * HALF + (2 * mp + mm) * 16) * DM + col0 + bj * HALF + n * 16;
;                         if (ai == 0 && mp == 0) bs[mm][bj][n] = bs0[mm][bj][n];
;                         else if (RES_BF16) { const u32x2 r = LDG(u32x2, xres + o_); bs[mm][bj][n] = (f32x4){bf_lo(r.x), bf_hi(r.x), bf_lo(r.y), bf_hi(r.y)}; }
;                         else bs[mm][bj][n] = LDG(f32x4, base + o_); }
;             asm volatile("" ::: "memory");
; #pragma unroll
;             for (int mm = 0; mm < 2; ++mm) { const int m = 2 * mp + mm; const int row = row0 + ai * HALF + m * 16; const size_t off = (size_t)row * DM + col0; float ss = 0.f;
; #pragma unroll
;                 for (int bj = 0; bj < 2; ++bj)
; #pragma unroll
;                     for (int n = 0; n < 2; ++n) { const f32x4 xn = bs[mm][bj][n] + gv[bj][n] * acc[ai][bj][m][n];
;                         if (RES_BF16) { u32x2 w_; w_.x = cvt_pk_bf16(xn[0], xn[1]); w_.y = cvt_pk_bf16(xn[2], xn[3]); STG(u32x2, xres + off + bj * HALF + n * 16) = w_; }
;                         else STG(f32x4, out + off + bj * HALF + n * 16) = xn;
;                         if (NEXT) { ss += (xn[0] * xn[0] + xn[1] * xn[1]) + (xn[2] * xn[2] + xn[3] * xn[3]); const f32x4 y = xn * gg[bj][n];
;                             u32x2 w; w.x = cvt_pk_bf16(y[0], y[1]); w.y = cvt_pk_bf16(y[2], y[3]); STG(u32x2, xg + off + bj * HALF + n * 16) = w; } }
;                 if (NEXT) { ss += swz_xor<16>(ss); auto rr = __builtin_amdgcn_permlane32_swap(__float_as_uint(ss), __float_as_uint(ss), false, false); ss = __uint_as_float(rr[0]) + __uint_as_float(rr[1]);
;                     if (fq == 0) atomicAdd(ssq + row, ss); } }
.LBB0_1204:
	s_or_b64 exec, exec, s[4:5]
	v_lshlrev_b64 v[130:131], 11, v[202:203]
	v_lshl_add_u64 v[130:131], v[130:131], 0, v[180:181]
	v_pk_fma_f32 v[128:129], v[128:129], v[64:65], v[160:161]
	v_pk_fma_f32 v[126:127], v[126:127], v[62:63], v[158:159]
	v_lshlrev_b32_e32 v132, 2, v130
	v_mul_f32_e32 v136, v127, v127
	v_mul_f32_e32 v137, v129, v129
	global_store_dwordx4 v132, v[126:129], s[40:41]
	v_fmac_f32_e32 v136, v126, v126
	v_fmac_f32_e32 v137, v128, v128
	v_pk_mul_f32 v[128:129], v[194:195], v[128:129]
	v_pk_mul_f32 v[126:127], v[196:197], v[126:127]
	v_pk_fma_f32 v[122:123], v[122:123], v[58:59], v[154:155]
	v_cvt_pk_bf16_f32 v248, v126, v127
	v_cvt_pk_bf16_f32 v249, v128, v129
	v_lshlrev_b32_e32 v128, 1, v130
	v_pk_fma_f32 v[124:125], v[124:125], v[60:61], v[156:157]
	v_mul_f32_e32 v126, v123, v123
	global_store_dwordx4 v132, v[122:125], s[40:41] offset:64
	v_fmac_f32_e32 v126, v122, v122
	v_mul_f32_e32 v127, v125, v125
	v_pk_mul_f32 v[122:123], v[192:193], v[122:123]
	v_pk_fma_f32 v[118:119], v[118:119], v[54:55], v[150:151]
	v_cvt_pk_bf16_f32 v250, v122, v123
	v_fmac_f32_e32 v127, v124, v124
	v_pk_mul_f32 v[124:125], v[190:191], v[124:125]
	v_pk_fma_f32 v[120:121], v[120:121], v[56:57], v[152:153]
	v_cvt_pk_bf16_f32 v251, v124, v125
	v_add_u32_e32 v252, v236, v128
	s_nop 0
	v_permlane16_swap_b32_e32 v248, v250
	v_permlane16_swap_b32_e32 v249, v251
	global_store_dwordx4 v252, v[248:251], s[42:43]
	s_nop 1
	v_mul_f32_e32 v122, v119, v119
	global_store_dwordx4 v132, v[118:121], s[40:41] offset:512
	v_fmac_f32_e32 v122, v118, v118
	v_mul_f32_e32 v123, v121, v121
	v_pk_mul_f32 v[118:119], v[188:189], v[118:119]
	v_fmac_f32_e32 v123, v120, v120
	v_pk_mul_f32 v[120:121], v[186:187], v[120:121]
	v_cvt_pk_bf16_f32 v248, v118, v119
	v_pk_fma_f32 v[116:117], v[116:117], v[52:53], v[148:149]
	v_cvt_pk_bf16_f32 v249, v120, v121
	v_pk_fma_f32 v[114:115], v[114:115], v[50:51], v[146:147]
	v_add_f32_e32 v136, v136, v137
	v_add_f32_e32 v126, v126, v127
	v_mul_f32_e32 v118, v115, v115
	v_mul_f32_e32 v119, v117, v117
	v_add_f32_e32 v126, v136, v126
	v_add_f32_e32 v122, v122, v123
	v_fmac_f32_e32 v118, v114, v114
	v_fmac_f32_e32 v119, v116, v116
	v_add_f32_e32 v122, v126, v122
	v_add_f32_e32 v118, v118, v119
	v_add_f32_e32 v118, v122, v118
	ds_swizzle_b32 v119, v118 offset:swizzle(SWAP,16)
	global_store_dwordx4 v132, v[114:117], s[40:41] offset:576
	s_nop 1
	v_pk_mul_f32 v[114:115], v[182:183], v[114:115]
	v_pk_mul_f32 v[116:117], v[184:185], v[116:117]
	v_cvt_pk_bf16_f32 v250, v114, v115
	s_nop 0
	v_cvt_pk_bf16_f32 v251, v116, v117
	v_add_u32_e32 v252, v236, v128
	s_nop 0
	v_permlane16_swap_b32_e32 v248, v250
	v_permlane16_swap_b32_e32 v249, v251
	global_store_dwordx4 v252, v[248:251], s[42:43] offset:256
	s_nop 1
	s_waitcnt lgkmcnt(0)
	v_add_f32_e32 v114, v118, v119
	v_mov_b32_e32 v115, v114
	s_nop 1
	v_permlane32_swap_b32_e32 v114, v115
	s_and_saveexec_b64 s[4:5], s[36:37]
	s_cbranch_execz .LBB0_1206
	v_add_f32_e32 v114, v114, v115
	global_atomic_add_f32 v[134:135], v114, off offset:64
.LBB0_1206:
	s_or_b64 exec, exec, s[4:5]
	v_or_b32_e32 v150, 32, v200
	v_ashrrev_i32_e32 v151, 31, v150
	v_lshlrev_b64 v[114:115], 13, v[150:151]
	v_lshl_add_u64 v[114:115], v[198:199], 0, v[114:115]
	global_load_dwordx4 v[138:141], v[114:115], off
	global_load_dwordx4 v[142:145], v[114:115], off offset:64
	global_load_dwordx4 v[146:149], v[114:115], off offset:512
	global_load_dwordx4 v[130:133], v[114:115], off offset:576
	v_or_b32_e32 v136, 48, v200
	v_ashrrev_i32_e32 v137, 31, v136
	v_lshlrev_b64 v[114:115], 13, v[136:137]
	v_lshl_add_u64 v[114:115], v[198:199], 0, v[114:115]
	global_load_dwordx4 v[126:129], v[114:115], off
	global_load_dwordx4 v[122:125], v[114:115], off offset:64
	global_load_dwordx4 v[118:121], v[114:115], off offset:512
	s_nop 0
	global_load_dwordx4 v[114:117], v[114:115], off offset:576
	v_lshlrev_b64 v[150:151], 11, v[150:151]
	v_lshl_add_u64 v[150:151], v[150:151], 0, v[180:181]
	s_waitcnt vmcnt(7)
	v_pk_fma_f32 v[112:113], v[112:113], v[64:65], v[140:141]
	v_pk_fma_f32 v[110:111], v[110:111], v[62:63], v[138:139]
	v_lshlrev_b32_e32 v138, 2, v150
	v_mul_f32_e32 v140, v111, v111
	v_mul_f32_e32 v141, v113, v113
	global_store_dwordx4 v138, v[110:113], s[40:41]
	v_fmac_f32_e32 v140, v110, v110
	v_fmac_f32_e32 v141, v112, v112
	v_pk_mul_f32 v[112:113], v[194:195], v[112:113]
	v_pk_mul_f32 v[110:111], v[196:197], v[110:111]
	s_waitcnt vmcnt(7)
	v_pk_fma_f32 v[106:107], v[106:107], v[58:59], v[142:143]
	v_add_f32_e32 v152, v140, v141
	v_cvt_pk_bf16_f32 v248, v110, v111
	v_cvt_pk_bf16_f32 v249, v112, v113
	v_lshlrev_b32_e32 v110, 1, v150
	v_pk_fma_f32 v[108:109], v[108:109], v[60:61], v[144:145]
	v_mul_f32_e32 v112, v107, v107
	global_store_dwordx4 v138, v[106:109], s[40:41] offset:64
	v_fmac_f32_e32 v112, v106, v106
	v_mul_f32_e32 v113, v109, v109
	v_pk_mul_f32 v[106:107], v[192:193], v[106:107]
	s_waitcnt vmcnt(7)
	v_pk_fma_f32 v[102:103], v[102:103], v[54:55], v[146:147]
	v_cvt_pk_bf16_f32 v250, v106, v107
	v_fmac_f32_e32 v113, v108, v108
	v_pk_mul_f32 v[108:109], v[190:191], v[108:109]
	v_pk_fma_f32 v[104:105], v[104:105], v[56:57], v[148:149]
	v_cvt_pk_bf16_f32 v251, v108, v109
	v_add_u32_e32 v252, v236, v110
	s_nop 0
	v_permlane16_swap_b32_e32 v248, v250
	v_permlane16_swap_b32_e32 v249, v251
	global_store_dwordx4 v252, v[248:251], s[42:43]
	s_nop 1
	v_mul_f32_e32 v106, v103, v103
	global_store_dwordx4 v138, v[102:105], s[40:41] offset:512
	v_fmac_f32_e32 v106, v102, v102
	v_mul_f32_e32 v107, v105, v105
	v_pk_mul_f32 v[102:103], v[188:189], v[102:103]
	v_fmac_f32_e32 v107, v104, v104
	v_pk_mul_f32 v[104:105], v[186:187], v[104:105]
	v_cvt_pk_bf16_f32 v248, v102, v103
	s_waitcnt vmcnt(8)
	v_pk_fma_f32 v[100:101], v[100:101], v[52:53], v[132:133]
	v_cvt_pk_bf16_f32 v249, v104, v105
	v_pk_fma_f32 v[98:99], v[98:99], v[50:51], v[130:131]
	v_add_f32_e32 v112, v112, v113
	v_mul_f32_e32 v102, v99, v99
	v_mul_f32_e32 v103, v101, v101
	v_add_f32_e32 v112, v152, v112
	v_add_f32_e32 v106, v106, v107
	v_fmac_f32_e32 v102, v98, v98
	v_fmac_f32_e32 v103, v100, v100
	v_add_f32_e32 v106, v112, v106
	global_store_dwordx4 v138, v[98:101], s[40:41] offset:576
	v_add_f32_e32 v102, v102, v103
	v_add_f32_e32 v102, v106, v102
	v_pk_mul_f32 v[98:99], v[182:183], v[98:99]
	v_pk_mul_f32 v[100:101], v[184:185], v[100:101]
	v_cvt_pk_bf16_f32 v250, v98, v99
	s_nop 0
	v_cvt_pk_bf16_f32 v251, v100, v101
	v_add_u32_e32 v252, v236, v110
	s_nop 0
	v_permlane16_swap_b32_e32 v248, v250
	v_permlane16_swap_b32_e32 v249, v251
	global_store_dwordx4 v252, v[248:251], s[42:43] offset:256
	s_nop 1
	ds_swizzle_b32 v98, v102 offset:swizzle(SWAP,16)
	s_waitcnt lgkmcnt(0)
	v_add_f32_e32 v98, v102, v98
	v_mov_b32_e32 v99, v98
	s_nop 1
	v_permlane32_swap_b32_e32 v98, v99
	s_and_saveexec_b64 s[4:5], s[36:37]
	s_mov_b32 s94, 0x2c000
	s_cbranch_execz .LBB0_1208
	v_add_f32_e32 v98, v98, v99
	global_atomic_add_f32 v[134:135], v98, off offset:128
; __device__ __forceinline__ unsigned cvt_pk_bf16(float lo, float hi) { unsigned r; asm volatile("v_cvt_pk_bf16_f32 %0, %1, %2" : "=v"(r) : "v"(lo), "v"(hi)); return r; }
; __device__ __forceinline__ float bf_lo(unsigned w) { return __uint_as_float(w << 16); }
;     __device__ __forceinline__ void operator()(const f32x4 (&acc)[2][2][4][2], const Unit& u, int wr, int wc, int fr, int fq) const {
;     ...
;         for (int mp = 0; mp < 2; ++mp) {
;             f32x4 bs[2][2][2];
; #pragma unroll
;             for (int mm = 0; mm < 2; ++mm)
; #pragma unroll
;                 for (int bj = 0; bj < 2; ++bj)
; #pragma unroll
;                     for (int n = 0; n < 2; ++n) { const size_t o_ = (size_t)(row0 + ai * HALF + (2 * mp + mm) * 16) * DM + col0 + bj * HALF + n * 16;
;                         if (ai == 0 && mp == 0) bs[mm][bj][n] = bs0[mm][bj][n];
;                         else if (RES_BF16) { const u32x2 r = LDG(u32x2, xres + o_); bs[mm][bj][n] = (f32x4){bf_lo(r.x), bf_hi(r.x), bf_lo(r.y), bf_hi(r.y)}; }
;                         else bs[mm][bj][n] = LDG(f32x4, base + o_); }
;             asm volatile("" ::: "memory");
; #pragma unroll
;             for (int mm = 0; mm < 2; ++mm) { const int m = 2 * mp + mm; const int row = row0 + ai * HALF + m * 16; const size_t off = (size_t)row * DM + col0; float ss = 0.f;
; #pragma unroll
;                 for (int bj = 0; bj < 2; ++bj)
; #pragma unroll
;                     for (int n = 0; n < 2; ++n) { const f32x4 xn = bs[mm][bj][n] + gv[bj][n] * acc[ai][bj][m][n];
;                         if (RES_BF16) { u32x2 w_; w_.x = cvt_pk_bf16(xn[0], xn[1]); w_.y = cvt_pk_bf16(xn[2], xn[3]); STG(u32x2, xres + off + bj * HALF + n * 16) = w_; }
;                         else STG(f32x4, out + off + bj * HALF + n * 16) = xn;
;                         if (NEXT) { ss += (xn[0] * xn[0] + xn[1] * xn[1]) + (xn[2] * xn[2] + xn[3] * xn[3]); const f32x4 y = xn * gg[bj][n];
;                             u32x2 w; w.x = cvt_pk_bf16(y[0], y[1]); w.y = cvt_pk_bf16(y[2], y[3]); STG(u32x2, xg + off + bj * HALF + n * 16) = w; } }
;                 if (NEXT) { ss += swz_xor<16>(ss); auto rr = __builtin_amdgcn_permlane32_swap(__float_as_uint(ss), __float_as_uint(ss), false, false); ss = __uint_as_float(rr[0]) + __uint_as_float(rr[1]);
;                     if (fq == 0) atomicAdd(ssq + row, ss); } }
.LBB0_1208:
	s_or_b64 exec, exec, s[4:5]
	v_lshlrev_b64 v[98:99], 11, v[136:137]
	v_lshl_add_u64 v[98:99], v[98:99], 0, v[180:181]
	s_waitcnt vmcnt(9)
	v_pk_fma_f32 v[96:97], v[96:97], v[64:65], v[128:129]
	v_pk_fma_f32 v[94:95], v[94:95], v[62:63], v[126:127]
	v_lshlrev_b32_e32 v100, 2, v98
	v_mul_f32_e32 v102, v95, v95
	v_mul_f32_e32 v103, v97, v97
	global_store_dwordx4 v100, v[94:97], s[40:41]
	v_fmac_f32_e32 v102, v94, v94
	v_fmac_f32_e32 v103, v96, v96
	v_pk_mul_f32 v[96:97], v[194:195], v[96:97]
	v_pk_mul_f32 v[94:95], v[196:197], v[94:95]
	s_waitcnt vmcnt(9)
	v_pk_fma_f32 v[90:91], v[90:91], v[58:59], v[122:123]
	v_cvt_pk_bf16_f32 v248, v94, v95
	v_cvt_pk_bf16_f32 v249, v96, v97
	v_lshlrev_b32_e32 v96, 1, v98
	v_pk_fma_f32 v[92:93], v[92:93], v[60:61], v[124:125]
	v_mul_f32_e32 v94, v91, v91
	global_store_dwordx4 v100, v[90:93], s[40:41] offset:64
	v_fmac_f32_e32 v94, v90, v90
	v_mul_f32_e32 v95, v93, v93
	v_pk_mul_f32 v[90:91], v[192:193], v[90:91]
	s_waitcnt vmcnt(9)
	v_pk_fma_f32 v[86:87], v[86:87], v[54:55], v[118:119]
	v_cvt_pk_bf16_f32 v250, v90, v91
	v_fmac_f32_e32 v95, v92, v92
	v_pk_mul_f32 v[92:93], v[190:191], v[92:93]
	v_pk_fma_f32 v[88:89], v[88:89], v[56:57], v[120:121]
	v_cvt_pk_bf16_f32 v251, v92, v93
	v_add_u32_e32 v252, v236, v96
	s_nop 0
	v_permlane16_swap_b32_e32 v248, v250
	v_permlane16_swap_b32_e32 v249, v251
	global_store_dwordx4 v252, v[248:251], s[42:43]
	s_nop 1
	v_mul_f32_e32 v90, v87, v87
	global_store_dwordx4 v100, v[86:89], s[40:41] offset:512
	v_fmac_f32_e32 v90, v86, v86
	v_mul_f32_e32 v91, v89, v89
	v_pk_mul_f32 v[86:87], v[188:189], v[86:87]
	v_fmac_f32_e32 v91, v88, v88
	v_pk_mul_f32 v[88:89], v[186:187], v[88:89]
	v_cvt_pk_bf16_f32 v248, v86, v87
	s_waitcnt vmcnt(10)
	v_pk_fma_f32 v[84:85], v[84:85], v[52:53], v[116:117]
	v_cvt_pk_bf16_f32 v249, v88, v89
	v_pk_fma_f32 v[82:83], v[82:83], v[50:51], v[114:115]
	v_add_f32_e32 v102, v102, v103
	v_add_f32_e32 v94, v94, v95
	v_mul_f32_e32 v86, v83, v83
	v_mul_f32_e32 v87, v85, v85
	v_add_f32_e32 v94, v102, v94
	v_add_f32_e32 v90, v90, v91
	v_fmac_f32_e32 v86, v82, v82
	v_fmac_f32_e32 v87, v84, v84
	v_add_f32_e32 v90, v94, v90
	v_add_f32_e32 v86, v86, v87
	v_add_f32_e32 v86, v90, v86
	ds_swizzle_b32 v87, v86 offset:swizzle(SWAP,16)
	global_store_dwordx4 v100, v[82:85], s[40:41] offset:576
	s_nop 1
	v_pk_mul_f32 v[82:83], v[182:183], v[82:83]
	v_pk_mul_f32 v[84:85], v[184:185], v[84:85]
	v_cvt_pk_bf16_f32 v250, v82, v83
	s_nop 0
	v_cvt_pk_bf16_f32 v251, v84, v85
	v_add_u32_e32 v252, v236, v96
	s_nop 0
	v_permlane16_swap_b32_e32 v248, v250
	v_permlane16_swap_b32_e32 v249, v251
	global_store_dwordx4 v252, v[248:251], s[42:43] offset:256
	s_nop 1
	s_waitcnt lgkmcnt(0)
	v_add_f32_e32 v82, v86, v87
	v_mov_b32_e32 v83, v82
	s_nop 1
	v_permlane32_swap_b32_e32 v82, v83
	s_and_saveexec_b64 s[4:5], s[36:37]
	s_cbranch_execz .LBB0_1210
	v_add_f32_e32 v82, v82, v83
	global_atomic_add_f32 v[134:135], v82, off offset:192
.LBB0_1210:
	s_or_b64 exec, exec, s[4:5]
	v_add_u32_e32 v116, 0x80, v200
	v_ashrrev_i32_e32 v117, 31, v116
	v_lshlrev_b64 v[82:83], 13, v[116:117]
	v_lshl_add_u64 v[82:83], v[198:199], 0, v[82:83]
	global_load_dwordx4 v[104:107], v[82:83], off
	global_load_dwordx4 v[108:111], v[82:83], off offset:64
	global_load_dwordx4 v[112:115], v[82:83], off offset:512
	global_load_dwordx4 v[98:101], v[82:83], off offset:576
	v_add_u32_e32 v102, 0x90, v200
	v_ashrrev_i32_e32 v103, 31, v102
	v_lshlrev_b64 v[82:83], 13, v[102:103]
	v_lshl_add_u64 v[82:83], v[198:199], 0, v[82:83]
	global_load_dwordx4 v[94:97], v[82:83], off
	global_load_dwordx4 v[90:93], v[82:83], off offset:64
	global_load_dwordx4 v[86:89], v[82:83], off offset:512
	s_nop 0
	global_load_dwordx4 v[82:85], v[82:83], off offset:576
	v_lshlrev_b64 v[116:117], 11, v[116:117]
	v_lshl_add_u64 v[116:117], v[116:117], 0, v[180:181]
	s_waitcnt vmcnt(7)
	v_pk_fma_f32 v[80:81], v[80:81], v[64:65], v[106:107]
	v_pk_fma_f32 v[78:79], v[78:79], v[62:63], v[104:105]
	v_lshlrev_b32_e32 v104, 2, v116
	v_mul_f32_e32 v106, v79, v79
	v_mul_f32_e32 v107, v81, v81
	global_store_dwordx4 v104, v[78:81], s[40:41]
	v_fmac_f32_e32 v106, v78, v78
	v_fmac_f32_e32 v107, v80, v80
	v_pk_mul_f32 v[80:81], v[194:195], v[80:81]
	v_pk_mul_f32 v[78:79], v[196:197], v[78:79]
	s_waitcnt vmcnt(7)
	v_pk_fma_f32 v[74:75], v[74:75], v[58:59], v[108:109]
	v_add_f32_e32 v118, v106, v107
	v_cvt_pk_bf16_f32 v248, v78, v79
	v_cvt_pk_bf16_f32 v249, v80, v81
	v_lshlrev_b32_e32 v78, 1, v116
	v_pk_fma_f32 v[76:77], v[76:77], v[60:61], v[110:111]
	v_mul_f32_e32 v80, v75, v75
	global_store_dwordx4 v104, v[74:77], s[40:41] offset:64
	v_fmac_f32_e32 v80, v74, v74
	v_mul_f32_e32 v81, v77, v77
	v_pk_mul_f32 v[74:75], v[192:193], v[74:75]
	s_waitcnt vmcnt(7)
	v_pk_fma_f32 v[70:71], v[70:71], v[54:55], v[112:113]
	v_cvt_pk_bf16_f32 v250, v74, v75
	v_fmac_f32_e32 v81, v76, v76
	v_pk_mul_f32 v[76:77], v[190:191], v[76:77]
	v_pk_fma_f32 v[72:73], v[72:73], v[56:57], v[114:115]
	v_cvt_pk_bf16_f32 v251, v76, v77
	v_add_u32_e32 v252, v236, v78
	s_nop 0
	v_permlane16_swap_b32_e32 v248, v250
	v_permlane16_swap_b32_e32 v249, v251
	global_store_dwordx4 v252, v[248:251], s[42:43]
	s_nop 1
	v_mul_f32_e32 v74, v71, v71
	global_store_dwordx4 v104, v[70:73], s[40:41] offset:512
	v_fmac_f32_e32 v74, v70, v70
	v_mul_f32_e32 v75, v73, v73
	v_pk_mul_f32 v[70:71], v[188:189], v[70:71]
	v_fmac_f32_e32 v75, v72, v72
	v_pk_mul_f32 v[72:73], v[186:187], v[72:73]
	v_cvt_pk_bf16_f32 v248, v70, v71
	s_waitcnt vmcnt(8)
	v_pk_fma_f32 v[68:69], v[68:69], v[52:53], v[100:101]
	v_cvt_pk_bf16_f32 v249, v72, v73
	v_pk_fma_f32 v[66:67], v[66:67], v[50:51], v[98:99]
	v_add_f32_e32 v80, v80, v81
	v_mul_f32_e32 v70, v67, v67
	v_mul_f32_e32 v71, v69, v69
	v_add_f32_e32 v80, v118, v80
	v_add_f32_e32 v74, v74, v75
	v_fmac_f32_e32 v70, v66, v66
	v_fmac_f32_e32 v71, v68, v68
	v_add_f32_e32 v74, v80, v74
	global_store_dwordx4 v104, v[66:69], s[40:41] offset:576
	v_add_f32_e32 v70, v70, v71
	v_add_f32_e32 v70, v74, v70
	v_pk_mul_f32 v[66:67], v[182:183], v[66:67]
	v_pk_mul_f32 v[68:69], v[184:185], v[68:69]
	v_cvt_pk_bf16_f32 v250, v66, v67
	s_nop 0
	v_cvt_pk_bf16_f32 v251, v68, v69
	v_add_u32_e32 v252, v236, v78
	s_nop 0
	v_permlane16_swap_b32_e32 v248, v250
	v_permlane16_swap_b32_e32 v249, v251
	global_store_dwordx4 v252, v[248:251], s[42:43] offset:256
	s_nop 1
	ds_swizzle_b32 v66, v70 offset:swizzle(SWAP,16)
	s_waitcnt lgkmcnt(0)
	v_add_f32_e32 v66, v70, v66
	v_mov_b32_e32 v67, v66
	s_nop 1
	v_permlane32_swap_b32_e32 v66, v67
	s_and_saveexec_b64 s[4:5], s[36:37]
	s_cbranch_execz .LBB0_1212
	v_add_f32_e32 v66, v66, v67
	global_atomic_add_f32 v[134:135], v66, off offset:512
; __device__ __forceinline__ unsigned cvt_pk_bf16(float lo, float hi) { unsigned r; asm volatile("v_cvt_pk_bf16_f32 %0, %1, %2" : "=v"(r) : "v"(lo), "v"(hi)); return r; }
; template <int O> __device__ __forceinline__ float swz_xor(float v) { return __int_as_float(__builtin_amdgcn_ds_swizzle(__float_as_int(v), (O << 10) | 0x1F)); }
;     __device__ __forceinline__ void operator()(const f32x4 (&acc)[2][2][4][2], const Unit& u, int wr, int wc, int fr, int fq) const {
;     ...
;             for (int mm = 0; mm < 2; ++mm) { const int m = 2 * mp + mm; const int row = row0 + ai * HALF + m * 16; const size_t off = (size_t)row * DM + col0; float ss = 0.f;
; #pragma unroll
;                 for (int bj = 0; bj < 2; ++bj)
; #pragma unroll
;                     for (int n = 0; n < 2; ++n) { const f32x4 xn = bs[mm][bj][n] + gv[bj][n] * acc[ai][bj][m][n];
;                         if (RES_BF16) { u32x2 w_; w_.x = cvt_pk_bf16(xn[0], xn[1]); w_.y = cvt_pk_bf16(xn[2], xn[3]); STG(u32x2, xres + off + bj * HALF + n * 16) = w_; }
;                         else STG(f32x4, out + off + bj * HALF + n * 16) = xn;
;                         if (NEXT) { ss += (xn[0] * xn[0] + xn[1] * xn[1]) + (xn[2] * xn[2] + xn[3] * xn[3]); const f32x4 y = xn * gg[bj][n];
;                             u32x2 w; w.x = cvt_pk_bf16(y[0], y[1]); w.y = cvt_pk_bf16(y[2], y[3]); STG(u32x2, xg + off + bj * HALF + n * 16) = w; } }
;                 if (NEXT) { ss += swz_xor<16>(ss); auto rr = __builtin_amdgcn_permlane32_swap(__float_as_uint(ss), __float_as_uint(ss), false, false); ss = __uint_as_float(rr[0]) + __uint_as_float(rr[1]);
;                     if (fq == 0) atomicAdd(ssq + row, ss); } }
.LBB0_1212:
	s_or_b64 exec, exec, s[4:5]
	v_lshlrev_b64 v[66:67], 11, v[102:103]
	v_lshl_add_u64 v[66:67], v[66:67], 0, v[180:181]
	s_waitcnt vmcnt(9)
	v_pk_fma_f32 v[48:49], v[48:49], v[64:65], v[96:97]
	v_pk_fma_f32 v[46:47], v[46:47], v[62:63], v[94:95]
	v_lshlrev_b32_e32 v68, 2, v66
	v_mul_f32_e32 v70, v47, v47
	v_mul_f32_e32 v71, v49, v49
	global_store_dwordx4 v68, v[46:49], s[40:41]
	v_fmac_f32_e32 v70, v46, v46
	v_fmac_f32_e32 v71, v48, v48
	v_pk_mul_f32 v[48:49], v[194:195], v[48:49]
	v_pk_mul_f32 v[46:47], v[196:197], v[46:47]
	s_waitcnt vmcnt(9)
	v_pk_fma_f32 v[42:43], v[42:43], v[58:59], v[90:91]
	v_cvt_pk_bf16_f32 v248, v46, v47
	v_cvt_pk_bf16_f32 v249, v48, v49
	v_lshlrev_b32_e32 v48, 1, v66
	v_pk_fma_f32 v[44:45], v[44:45], v[60:61], v[92:93]
	v_mul_f32_e32 v46, v43, v43
	global_store_dwordx4 v68, v[42:45], s[40:41] offset:64
	v_fmac_f32_e32 v46, v42, v42
	v_mul_f32_e32 v47, v45, v45
	v_pk_mul_f32 v[42:43], v[192:193], v[42:43]
	s_waitcnt vmcnt(9)
	v_pk_fma_f32 v[38:39], v[38:39], v[54:55], v[86:87]
	v_cvt_pk_bf16_f32 v250, v42, v43
	v_fmac_f32_e32 v47, v44, v44
	v_pk_mul_f32 v[44:45], v[190:191], v[44:45]
	v_pk_fma_f32 v[40:41], v[40:41], v[56:57], v[88:89]
	v_cvt_pk_bf16_f32 v251, v44, v45
	v_add_u32_e32 v252, v236, v48
	s_nop 0
	v_permlane16_swap_b32_e32 v248, v250
	v_permlane16_swap_b32_e32 v249, v251
	global_store_dwordx4 v252, v[248:251], s[42:43]
	s_nop 1
	v_mul_f32_e32 v42, v39, v39
	global_store_dwordx4 v68, v[38:41], s[40:41] offset:512
	v_fmac_f32_e32 v42, v38, v38
	v_mul_f32_e32 v43, v41, v41
	v_pk_mul_f32 v[38:39], v[188:189], v[38:39]
	v_fmac_f32_e32 v43, v40, v40
	v_pk_mul_f32 v[40:41], v[186:187], v[40:41]
	v_cvt_pk_bf16_f32 v248, v38, v39
	s_waitcnt vmcnt(10)
	v_pk_fma_f32 v[36:37], v[36:37], v[52:53], v[84:85]
	v_cvt_pk_bf16_f32 v249, v40, v41
	v_pk_fma_f32 v[34:35], v[34:35], v[50:51], v[82:83]
	v_add_f32_e32 v70, v70, v71
	v_add_f32_e32 v46, v46, v47
	v_mul_f32_e32 v38, v35, v35
	v_mul_f32_e32 v39, v37, v37
	v_add_f32_e32 v46, v70, v46
	v_add_f32_e32 v42, v42, v43
	v_fmac_f32_e32 v38, v34, v34
	v_fmac_f32_e32 v39, v36, v36
	v_add_f32_e32 v42, v46, v42
	v_add_f32_e32 v38, v38, v39
	v_add_f32_e32 v38, v42, v38
	ds_swizzle_b32 v39, v38 offset:swizzle(SWAP,16)
	global_store_dwordx4 v68, v[34:37], s[40:41] offset:576
	s_nop 1
	v_pk_mul_f32 v[34:35], v[182:183], v[34:35]
	v_pk_mul_f32 v[36:37], v[184:185], v[36:37]
	v_cvt_pk_bf16_f32 v250, v34, v35
	s_nop 0
	v_cvt_pk_bf16_f32 v251, v36, v37
	v_add_u32_e32 v252, v236, v48
	s_nop 0
	v_permlane16_swap_b32_e32 v248, v250
	v_permlane16_swap_b32_e32 v249, v251
	global_store_dwordx4 v252, v[248:251], s[42:43] offset:256
	s_nop 1
	s_waitcnt lgkmcnt(0)
	v_add_f32_e32 v34, v38, v39
	v_mov_b32_e32 v35, v34
	s_nop 1
	v_permlane32_swap_b32_e32 v34, v35
	s_and_saveexec_b64 s[4:5], s[36:37]
	s_cbranch_execz .LBB0_1214
	v_add_f32_e32 v34, v34, v35
	global_atomic_add_f32 v[134:135], v34, off offset:576
; __device__ __forceinline__ unsigned cvt_pk_bf16(float lo, float hi) { unsigned r; asm volatile("v_cvt_pk_bf16_f32 %0, %1, %2" : "=v"(r) : "v"(lo), "v"(hi)); return r; }
; __device__ __forceinline__ float bf_lo(unsigned w) { return __uint_as_float(w << 16); }
;     __device__ __forceinline__ void operator()(const f32x4 (&acc)[2][2][4][2], const Unit& u, int wr, int wc, int fr, int fq) const {
;     ...
;         for (int mp = 0; mp < 2; ++mp) {
;             f32x4 bs[2][2][2];
; #pragma unroll
;             for (int mm = 0; mm < 2; ++mm)
; #pragma unroll
;                 for (int bj = 0; bj < 2; ++bj)
; #pragma unroll
;                     for (int n = 0; n < 2; ++n) { const size_t o_ = (size_t)(row0 + ai * HALF + (2 * mp + mm) * 16) * DM + col0 + bj * HALF + n * 16;
;                         if (ai == 0 && mp == 0) bs[mm][bj][n] = bs0[mm][bj][n];
;                         else if (RES_BF16) { const u32x2 r = LDG(u32x2, xres + o_); bs[mm][bj][n] = (f32x4){bf_lo(r.x), bf_hi(r.x), bf_lo(r.y), bf_hi(r.y)}; }
;                         else bs[mm][bj][n] = LDG(f32x4, base + o_); }
;             asm volatile("" ::: "memory");
; #pragma unroll
;             for (int mm = 0; mm < 2; ++mm) { const int m = 2 * mp + mm; const int row = row0 + ai * HALF + m * 16; const size_t off = (size_t)row * DM + col0; float ss = 0.f;
; #pragma unroll
;                 for (int bj = 0; bj < 2; ++bj)
; #pragma unroll
;                     for (int n = 0; n < 2; ++n) { const f32x4 xn = bs[mm][bj][n] + gv[bj][n] * acc[ai][bj][m][n];
;                         if (RES_BF16) { u32x2 w_; w_.x = cvt_pk_bf16(xn[0], xn[1]); w_.y = cvt_pk_bf16(xn[2], xn[3]); STG(u32x2, xres + off + bj * HALF + n * 16) = w_; }
;                         else STG(f32x4, out + off + bj * HALF + n * 16) = xn;
;                         if (NEXT) { ss += (xn[0] * xn[0] + xn[1] * xn[1]) + (xn[2] * xn[2] + xn[3] * xn[3]); const f32x4 y = xn * gg[bj][n];
;                             u32x2 w; w.x = cvt_pk_bf16(y[0], y[1]); w.y = cvt_pk_bf16(y[2], y[3]); STG(u32x2, xg + off + bj * HALF + n * 16) = w; } }
;                 if (NEXT) { ss += swz_xor<16>(ss); auto rr = __builtin_amdgcn_permlane32_swap(__float_as_uint(ss), __float_as_uint(ss), false, false); ss = __uint_as_float(rr[0]) + __uint_as_float(rr[1]);
;                     if (fq == 0) atomicAdd(ssq + row, ss); } }
.LBB0_1214:
	s_or_b64 exec, exec, s[4:5]
	v_add_u32_e32 v84, 0xa0, v200
	v_ashrrev_i32_e32 v85, 31, v84
	v_lshlrev_b64 v[34:35], 13, v[84:85]
	v_lshl_add_u64 v[34:35], v[198:199], 0, v[34:35]
	global_load_dwordx4 v[72:75], v[34:35], off
	global_load_dwordx4 v[76:79], v[34:35], off offset:64
	global_load_dwordx4 v[80:83], v[34:35], off offset:512
	global_load_dwordx4 v[66:69], v[34:35], off offset:576
	v_add_u32_e32 v70, 0xb0, v200
	v_ashrrev_i32_e32 v71, 31, v70
	v_lshlrev_b64 v[34:35], 13, v[70:71]
	v_lshl_add_u64 v[34:35], v[198:199], 0, v[34:35]
	global_load_dwordx4 v[46:49], v[34:35], off
	global_load_dwordx4 v[42:45], v[34:35], off offset:64
	global_load_dwordx4 v[38:41], v[34:35], off offset:512
	s_nop 0
	global_load_dwordx4 v[34:37], v[34:35], off offset:576
	v_lshlrev_b64 v[84:85], 11, v[84:85]
	v_lshl_add_u64 v[84:85], v[84:85], 0, v[180:181]
	s_waitcnt vmcnt(7)
	v_pk_fma_f32 v[32:33], v[32:33], v[64:65], v[74:75]
	v_pk_fma_f32 v[30:31], v[30:31], v[62:63], v[72:73]
	v_lshlrev_b32_e32 v72, 2, v84
	v_mul_f32_e32 v74, v31, v31
	v_mul_f32_e32 v75, v33, v33
	global_store_dwordx4 v72, v[30:33], s[40:41]
	v_fmac_f32_e32 v74, v30, v30
	v_fmac_f32_e32 v75, v32, v32
	v_pk_mul_f32 v[32:33], v[194:195], v[32:33]
	v_pk_mul_f32 v[30:31], v[196:197], v[30:31]
	s_waitcnt vmcnt(7)
	v_pk_fma_f32 v[26:27], v[26:27], v[58:59], v[76:77]
	v_add_f32_e32 v86, v74, v75
	v_cvt_pk_bf16_f32 v248, v30, v31
	v_cvt_pk_bf16_f32 v249, v32, v33
	v_lshlrev_b32_e32 v30, 1, v84
	v_pk_fma_f32 v[28:29], v[28:29], v[60:61], v[78:79]
	v_mul_f32_e32 v32, v27, v27
	global_store_dwordx4 v72, v[26:29], s[40:41] offset:64
	v_fmac_f32_e32 v32, v26, v26
	v_mul_f32_e32 v33, v29, v29
	v_pk_mul_f32 v[26:27], v[192:193], v[26:27]
	s_waitcnt vmcnt(7)
	v_pk_fma_f32 v[22:23], v[22:23], v[54:55], v[80:81]
	v_cvt_pk_bf16_f32 v250, v26, v27
	v_fmac_f32_e32 v33, v28, v28
	v_pk_mul_f32 v[28:29], v[190:191], v[28:29]
	v_pk_fma_f32 v[24:25], v[24:25], v[56:57], v[82:83]
	v_cvt_pk_bf16_f32 v251, v28, v29
	v_add_u32_e32 v252, v236, v30
	s_nop 0
	v_permlane16_swap_b32_e32 v248, v250
	v_permlane16_swap_b32_e32 v249, v251
	global_store_dwordx4 v252, v[248:251], s[42:43]
	s_nop 1
	v_mul_f32_e32 v26, v23, v23
	global_store_dwordx4 v72, v[22:25], s[40:41] offset:512
	v_fmac_f32_e32 v26, v22, v22
	v_mul_f32_e32 v27, v25, v25
	v_pk_mul_f32 v[22:23], v[188:189], v[22:23]
	v_fmac_f32_e32 v27, v24, v24
	v_pk_mul_f32 v[24:25], v[186:187], v[24:25]
	v_cvt_pk_bf16_f32 v248, v22, v23
	s_waitcnt vmcnt(8)
	v_pk_fma_f32 v[20:21], v[20:21], v[52:53], v[68:69]
	v_cvt_pk_bf16_f32 v249, v24, v25
	v_pk_fma_f32 v[18:19], v[18:19], v[50:51], v[66:67]
	v_add_f32_e32 v32, v32, v33
	v_mul_f32_e32 v22, v19, v19
	v_mul_f32_e32 v23, v21, v21
	v_add_f32_e32 v32, v86, v32
	v_add_f32_e32 v26, v26, v27
	v_fmac_f32_e32 v22, v18, v18
	v_fmac_f32_e32 v23, v20, v20
	v_add_f32_e32 v26, v32, v26
	global_store_dwordx4 v72, v[18:21], s[40:41] offset:576
	v_add_f32_e32 v22, v22, v23
	v_add_f32_e32 v22, v26, v22
	v_pk_mul_f32 v[18:19], v[182:183], v[18:19]
	v_pk_mul_f32 v[20:21], v[184:185], v[20:21]
	v_cvt_pk_bf16_f32 v250, v18, v19
	s_nop 0
	v_cvt_pk_bf16_f32 v251, v20, v21
	v_add_u32_e32 v252, v236, v30
	s_nop 0
	v_permlane16_swap_b32_e32 v248, v250
	v_permlane16_swap_b32_e32 v249, v251
	global_store_dwordx4 v252, v[248:251], s[42:43] offset:256
	s_nop 1
	ds_swizzle_b32 v18, v22 offset:swizzle(SWAP,16)
	s_waitcnt lgkmcnt(0)
	v_add_f32_e32 v18, v22, v18
	v_mov_b32_e32 v19, v18
	s_nop 1
	v_permlane32_swap_b32_e32 v18, v19
	s_and_saveexec_b64 s[4:5], s[36:37]
	s_cbranch_execz .LBB0_1216
	v_add_f32_e32 v18, v18, v19
	global_atomic_add_f32 v[134:135], v18, off offset:640
.LBB0_1216:
	s_or_b64 exec, exec, s[4:5]
	v_lshlrev_b64 v[18:19], 11, v[70:71]
	v_lshl_add_u64 v[18:19], v[18:19], 0, v[180:181]
	s_waitcnt vmcnt(9)
	v_pk_fma_f32 v[16:17], v[16:17], v[64:65], v[48:49]
	v_pk_fma_f32 v[14:15], v[14:15], v[62:63], v[46:47]
	v_lshlrev_b32_e32 v20, 2, v18
	v_mul_f32_e32 v22, v15, v15
	v_mul_f32_e32 v23, v17, v17
	global_store_dwordx4 v20, v[14:17], s[40:41]
	v_fmac_f32_e32 v22, v14, v14
	v_fmac_f32_e32 v23, v16, v16
	v_pk_mul_f32 v[16:17], v[194:195], v[16:17]
	v_pk_mul_f32 v[14:15], v[196:197], v[14:15]
	s_waitcnt vmcnt(9)
	v_pk_fma_f32 v[10:11], v[10:11], v[58:59], v[42:43]
	v_cvt_pk_bf16_f32 v248, v14, v15
	v_cvt_pk_bf16_f32 v249, v16, v17
	v_lshlrev_b32_e32 v16, 1, v18
	v_pk_fma_f32 v[12:13], v[12:13], v[60:61], v[44:45]
	v_mul_f32_e32 v14, v11, v11
	global_store_dwordx4 v20, v[10:13], s[40:41] offset:64
	v_fmac_f32_e32 v14, v10, v10
	v_mul_f32_e32 v15, v13, v13
	v_pk_mul_f32 v[10:11], v[192:193], v[10:11]
	s_waitcnt vmcnt(9)
	v_pk_fma_f32 v[6:7], v[6:7], v[54:55], v[38:39]
	v_cvt_pk_bf16_f32 v250, v10, v11
	v_fmac_f32_e32 v15, v12, v12
	v_pk_mul_f32 v[12:13], v[190:191], v[12:13]
	v_pk_fma_f32 v[8:9], v[8:9], v[56:57], v[40:41]
	v_cvt_pk_bf16_f32 v251, v12, v13
	v_add_u32_e32 v252, v236, v16
	s_nop 0
	v_permlane16_swap_b32_e32 v248, v250
	v_permlane16_swap_b32_e32 v249, v251
	global_store_dwordx4 v252, v[248:251], s[42:43]
	s_nop 1
	v_mul_f32_e32 v10, v7, v7
	global_store_dwordx4 v20, v[6:9], s[40:41] offset:512
	v_fmac_f32_e32 v10, v6, v6
	v_mul_f32_e32 v11, v9, v9
	v_pk_mul_f32 v[6:7], v[188:189], v[6:7]
	v_fmac_f32_e32 v11, v8, v8
	v_pk_mul_f32 v[8:9], v[186:187], v[8:9]
	v_cvt_pk_bf16_f32 v248, v6, v7
	s_waitcnt vmcnt(10)
	v_pk_fma_f32 v[4:5], v[4:5], v[52:53], v[36:37]
	v_cvt_pk_bf16_f32 v249, v8, v9
	v_pk_fma_f32 v[2:3], v[2:3], v[50:51], v[34:35]
	v_add_f32_e32 v22, v22, v23
	v_add_f32_e32 v14, v14, v15
	v_mul_f32_e32 v6, v3, v3
	v_mul_f32_e32 v7, v5, v5
	v_add_f32_e32 v14, v22, v14
	v_add_f32_e32 v10, v10, v11
	v_fmac_f32_e32 v6, v2, v2
	v_fmac_f32_e32 v7, v4, v4
	v_add_f32_e32 v10, v14, v10
	v_add_f32_e32 v6, v6, v7
	v_add_f32_e32 v6, v10, v6
	ds_swizzle_b32 v7, v6 offset:swizzle(SWAP,16)
	global_store_dwordx4 v20, v[2:5], s[40:41] offset:576
	s_nop 1
	v_pk_mul_f32 v[2:3], v[182:183], v[2:3]
	v_pk_mul_f32 v[4:5], v[184:185], v[4:5]
	v_cvt_pk_bf16_f32 v250, v2, v3
	s_nop 0
	v_cvt_pk_bf16_f32 v251, v4, v5
	v_add_u32_e32 v252, v236, v16
	s_nop 0
	v_permlane16_swap_b32_e32 v248, v250
	v_permlane16_swap_b32_e32 v249, v251
	global_store_dwordx4 v252, v[248:251], s[42:43] offset:256
	s_nop 1
	s_waitcnt lgkmcnt(0)
	v_add_f32_e32 v2, v6, v7
	v_mov_b32_e32 v3, v2
	s_nop 1
	v_permlane32_swap_b32_e32 v2, v3
	s_and_saveexec_b64 s[4:5], s[36:37]
	s_cbranch_execz .LBB0_1218
	v_add_f32_e32 v2, v2, v3
	global_atomic_add_f32 v[134:135], v2, off offset:704

; __device__ __forceinline__ unsigned cvt_pk_bf16(float lo, float hi) { unsigned r; asm volatile("v_cvt_pk_bf16_f32 %0, %1, %2" : "=v"(r) : "v"(lo), "v"(hi)); return r; }
; __device__ __forceinline__ f32x2 gelu_pk(f32x2 v) {
;     const f32x2 av = __builtin_elementwise_abs(v), d = av * 0.2316418882f + 1.0f;
;     f32x2 t; t.x = __builtin_amdgcn_rcpf(d.x); t.y = __builtin_amdgcn_rcpf(d.y);
;     f32x2 q = t * 0.5307027145f + (-0.7265760135f); q = q * t + 0.7107068705f; q = q * t + (-0.142248368f); q = q * t + 0.127414796f; q = q * t;
;     const f32x2 s = (v * v) * (-0.72134752044f);
;     f32x2 e; e.x = __builtin_amdgcn_exp2f(s.x); e.y = __builtin_amdgcn_exp2f(s.y);
;     const f32x2 h = 0.5f - q * e;
;     return av * h + v * 0.5f;
;     __device__ __forceinline__ void operator()(f32x4 (&acc)[2][2][4][2], const Unit& u, int wr, int wc, int fr, int fq) const {
;     ...
;             for (int n = 0; n < 2; ++n) {
;                 f32x4 pv = (am == 0) ? pvx[n] : acc[(am - 1 < 0 ? 0 : am - 1) >> 2][0][(am - 1 < 0 ? 0 : am - 1) & 3][n];
;                 f32x4 nv = (am == 7) ? nvx[n] : acc[(am + 1 > 7 ? 7 : am + 1) >> 2][0][(am + 1 > 7 ? 7 : am + 1) & 3][n];
;                 f32x4 v = cbv[n] + w0[n] * pv + w1[n] * acc[ai][0][m][n] + w2[n] * nv;
;                 if (edge) {
;                     asm volatile("" ::: "memory");
;                     const f32x4 z = {0.f, 0.f, 0.f, 0.f}; const f32x4 pz = first ? z : pv, nz = lastt ? z : nv;
;                     v = cbv[n] + w0[n] * pz + w1[n] * acc[ai][0][m][n] + w2[n] * nz; }
;                 const f32x2 g0 = gelu_pk((f32x2){v[0], v[1]}), g1 = gelu_pk((f32x2){v[2], v[3]});
;                 const f32x4 bb = acc[ai][1][m][n];
;                 const unsigned lo = cvt_pk_bf16(g0.x * bb[0], g0.y * bb[1]), hi = cvt_pk_bf16(g1.x * bb[2], g1.y * bb[3]);
;                 if (n == 0) { w.x = lo; w.y = hi; } else { w.z = lo; w.w = hi; }
;             }
;             if (ok) STG(u32x4, G + (size_t)tok * DFF + f0) = w;
.LBB0_1308:
	s_waitcnt lgkmcnt(5)
	v_pk_fma_f32 v[176:177], v[86:87], v[176:177], v[90:91]
	s_waitcnt lgkmcnt(1)
	v_pk_fma_f32 v[164:165], v[88:89], v[190:191], v[92:93]
	v_pk_fma_f32 v[176:177], v[142:143], v[74:75], v[176:177]
	v_pk_fma_f32 v[164:165], v[144:145], v[76:77], v[164:165]
	v_pk_fma_f32 v[160:161], v[78:79], v[160:161], v[176:177]
	v_pk_fma_f32 v[162:163], v[80:81], v[162:163], v[164:165]
	v_and_b32_e32 v165, 0x7fffffff, v161
	v_and_b32_e32 v164, 0x7fffffff, v160
	v_pk_fma_f32 v[176:177], v[164:165], s[78:79], 1.0 op_sel_hi:[1,0,0]
	v_mov_b64_e32 v[190:191], s[82:83]
	v_rcp_f32_e32 v176, v176
	v_rcp_f32_e32 v177, v177
	v_pk_mul_f32 v[194:195], v[160:161], v[160:161]
	s_mov_b32 s4, 0xa000
	v_pk_mul_f32 v[194:195], v[194:195], s[90:91] op_sel_hi:[1,0]
	v_pk_fma_f32 v[192:193], v[176:177], s[80:81], v[190:191] op_sel_hi:[1,0,0]
	v_exp_f32_e32 v194, v194
	v_pk_fma_f32 v[192:193], v[176:177], v[192:193], s[84:85] op_sel_hi:[1,1,0]
	v_exp_f32_e32 v195, v195
	v_pk_fma_f32 v[192:193], v[176:177], v[192:193], s[86:87] op_sel_hi:[1,1,0]
	v_cmp_gt_i32_e32 vcc, s4, v203
	v_pk_fma_f32 v[192:193], v[176:177], v[192:193], s[88:89] op_sel_hi:[1,1,0]
	s_and_b64 s[6:7], s[36:37], vcc
	v_pk_mul_f32 v[176:177], v[176:177], v[192:193]
	v_pk_mul_f32 v[192:193], v[162:163], v[162:163]
	v_pk_fma_f32 v[176:177], v[194:195], v[176:177], 0.5 op_sel_hi:[1,1,0] neg_lo:[1,0,0] neg_hi:[1,0,0]
	s_nop 0
	v_pk_mul_f32 v[164:165], v[164:165], v[176:177]
	s_nop 0
	v_pk_fma_f32 v[160:161], v[160:161], 0.5, v[164:165] op_sel_hi:[1,0,1]
	v_and_b32_e32 v165, 0x7fffffff, v163
	v_and_b32_e32 v164, 0x7fffffff, v162
	v_pk_fma_f32 v[176:177], v[164:165], s[78:79], 1.0 op_sel_hi:[1,0,0]
	v_mul_f32_e32 v154, v154, v160
	v_rcp_f32_e32 v176, v176
	v_rcp_f32_e32 v177, v177
	v_mul_f32_e32 v155, v155, v161
	v_cvt_pk_bf16_f32 v160, v154, v155
	v_pk_fma_f32 v[190:191], v[176:177], s[80:81], v[190:191] op_sel_hi:[1,0,0]
	s_nop 0
	v_pk_fma_f32 v[190:191], v[176:177], v[190:191], s[84:85] op_sel_hi:[1,1,0]
	s_nop 0
	v_pk_fma_f32 v[190:191], v[176:177], v[190:191], s[86:87] op_sel_hi:[1,1,0]
	s_nop 0
	v_pk_fma_f32 v[190:191], v[176:177], v[190:191], s[88:89] op_sel_hi:[1,1,0]
	s_nop 0
	v_pk_mul_f32 v[176:177], v[176:177], v[190:191]
	v_pk_mul_f32 v[190:191], v[192:193], s[90:91] op_sel_hi:[1,0]
	s_nop 0
	v_exp_f32_e32 v190, v190
	v_exp_f32_e32 v191, v191
	s_nop 0
	v_pk_fma_f32 v[176:177], v[190:191], v[176:177], 0.5 op_sel_hi:[1,1,0] neg_lo:[1,0,0] neg_hi:[1,0,0]
	s_nop 0
	v_pk_mul_f32 v[164:165], v[164:165], v[176:177]
	s_nop 0
	v_pk_fma_f32 v[162:163], v[162:163], 0.5, v[164:165] op_sel_hi:[1,0,1]
	s_nop 0
	v_mul_f32_e32 v154, v156, v162
	v_mul_f32_e32 v155, v157, v163
	v_cvt_pk_bf16_f32 v161, v154, v155
	s_and_saveexec_b64 s[4:5], s[6:7]
	s_cbranch_execz .LBB0_1310
	v_mul_u32_u24_e32 v154, s33, v203
	v_lshl_add_u32 v154, v166, 1, v154
	global_store_dwordx4 v154, v[158:161], s[62:63]

; __device__ __forceinline__ unsigned cvt_pk_bf16(float lo, float hi) { unsigned r; asm volatile("v_cvt_pk_bf16_f32 %0, %1, %2" : "=v"(r) : "v"(lo), "v"(hi)); return r; }
; __device__ __forceinline__ f32x2 gelu_pk(f32x2 v) {
;     const f32x2 av = __builtin_elementwise_abs(v), d = av * 0.2316418882f + 1.0f;
;     f32x2 t; t.x = __builtin_amdgcn_rcpf(d.x); t.y = __builtin_amdgcn_rcpf(d.y);
;     f32x2 q = t * 0.5307027145f + (-0.7265760135f); q = q * t + 0.7107068705f; q = q * t + (-0.142248368f); q = q * t + 0.127414796f; q = q * t;
;     const f32x2 s = (v * v) * (-0.72134752044f);
;     f32x2 e; e.x = __builtin_amdgcn_exp2f(s.x); e.y = __builtin_amdgcn_exp2f(s.y);
;     const f32x2 h = 0.5f - q * e;
;     return av * h + v * 0.5f;
;     __device__ __forceinline__ void operator()(f32x4 (&acc)[2][2][4][2], const Unit& u, int wr, int wc, int fr, int fq) const {
;     ...
;             for (int n = 0; n < 2; ++n) {
;                 f32x4 pv = (am == 0) ? pvx[n] : acc[(am - 1 < 0 ? 0 : am - 1) >> 2][0][(am - 1 < 0 ? 0 : am - 1) & 3][n];
;                 f32x4 nv = (am == 7) ? nvx[n] : acc[(am + 1 > 7 ? 7 : am + 1) >> 2][0][(am + 1 > 7 ? 7 : am + 1) & 3][n];
;                 f32x4 v = cbv[n] + w0[n] * pv + w1[n] * acc[ai][0][m][n] + w2[n] * nv;
;                 if (edge) {
;                     asm volatile("" ::: "memory");
;                     const f32x4 z = {0.f, 0.f, 0.f, 0.f}; const f32x4 pz = first ? z : pv, nz = lastt ? z : nv;
;                     v = cbv[n] + w0[n] * pz + w1[n] * acc[ai][0][m][n] + w2[n] * nz; }
;                 const f32x2 g0 = gelu_pk((f32x2){v[0], v[1]}), g1 = gelu_pk((f32x2){v[2], v[3]});
;                 const f32x4 bb = acc[ai][1][m][n];
;                 const unsigned lo = cvt_pk_bf16(g0.x * bb[0], g0.y * bb[1]), hi = cvt_pk_bf16(g1.x * bb[2], g1.y * bb[3]);
;                 if (n == 0) { w.x = lo; w.y = hi; } else { w.z = lo; w.w = hi; }
;             }
;             if (ok) STG(u32x4, G + (size_t)tok * DFF + f0) = w;
.LBB0_1314:
	v_pk_fma_f32 v[142:143], v[86:87], v[142:143], v[90:91]
	v_mov_b64_e32 v[152:153], s[82:83]
	v_pk_fma_f32 v[142:143], v[126:127], v[74:75], v[142:143]
	v_pk_fma_f32 v[144:145], v[88:89], v[144:145], v[92:93]
	v_pk_fma_f32 v[142:143], v[94:95], v[78:79], v[142:143]
	v_pk_fma_f32 v[144:145], v[128:129], v[76:77], v[144:145]
	v_and_b32_e32 v149, 0x7fffffff, v143
	v_and_b32_e32 v148, 0x7fffffff, v142
	v_pk_fma_f32 v[150:151], v[148:149], s[78:79], 1.0 op_sel_hi:[1,0,0]
	v_pk_mul_f32 v[156:157], v[142:143], v[142:143]
	v_rcp_f32_e32 v150, v150
	v_rcp_f32_e32 v151, v151
	v_pk_mul_f32 v[156:157], v[156:157], s[90:91] op_sel_hi:[1,0]
	v_pk_fma_f32 v[144:145], v[96:97], v[80:81], v[144:145]
	v_exp_f32_e32 v156, v156
	v_pk_fma_f32 v[154:155], v[150:151], s[80:81], v[152:153] op_sel_hi:[1,0,0]
	v_exp_f32_e32 v157, v157
	v_pk_fma_f32 v[154:155], v[150:151], v[154:155], s[84:85] op_sel_hi:[1,1,0]
	s_mov_b32 s4, 0x9fff
	v_pk_fma_f32 v[154:155], v[150:151], v[154:155], s[86:87] op_sel_hi:[1,1,0]
	v_cmp_gt_i32_e32 vcc, s4, v203
	v_pk_fma_f32 v[154:155], v[150:151], v[154:155], s[88:89] op_sel_hi:[1,1,0]
	s_nop 0
	v_pk_mul_f32 v[150:151], v[150:151], v[154:155]
	v_pk_mul_f32 v[154:155], v[144:145], v[144:145]
	v_pk_fma_f32 v[150:151], v[156:157], v[150:151], 0.5 op_sel_hi:[1,1,0] neg_lo:[1,0,0] neg_hi:[1,0,0]
	s_nop 0
	v_pk_mul_f32 v[148:149], v[148:149], v[150:151]
	s_nop 0
	v_pk_fma_f32 v[142:143], v[142:143], 0.5, v[148:149] op_sel_hi:[1,0,1]
	v_and_b32_e32 v149, 0x7fffffff, v145
	v_and_b32_e32 v148, 0x7fffffff, v144
	v_pk_fma_f32 v[150:151], v[148:149], s[78:79], 1.0 op_sel_hi:[1,0,0]
	v_mul_f32_e32 v138, v138, v142
	v_rcp_f32_e32 v150, v150
	v_rcp_f32_e32 v151, v151
	v_mul_f32_e32 v139, v139, v143
	v_pk_fma_f32 v[152:153], v[150:151], s[80:81], v[152:153] op_sel_hi:[1,0,0]
	s_nop 0
	v_pk_fma_f32 v[152:153], v[150:151], v[152:153], s[84:85] op_sel_hi:[1,1,0]
	s_nop 0
	v_pk_fma_f32 v[152:153], v[150:151], v[152:153], s[86:87] op_sel_hi:[1,1,0]
	s_nop 0
	v_pk_fma_f32 v[152:153], v[150:151], v[152:153], s[88:89] op_sel_hi:[1,1,0]
	s_nop 0
	v_pk_mul_f32 v[150:151], v[150:151], v[152:153]
	v_pk_mul_f32 v[152:153], v[154:155], s[90:91] op_sel_hi:[1,0]
	s_nop 0
	v_exp_f32_e32 v152, v152
	v_exp_f32_e32 v153, v153
	s_nop 0
	v_pk_fma_f32 v[150:151], v[152:153], v[150:151], 0.5 op_sel_hi:[1,1,0] neg_lo:[1,0,0] neg_hi:[1,0,0]
	s_nop 0
	v_pk_mul_f32 v[148:149], v[148:149], v[150:151]
	s_nop 0
	v_pk_fma_f32 v[144:145], v[144:145], 0.5, v[148:149] op_sel_hi:[1,0,1]
	v_cvt_pk_bf16_f32 v148, v138, v139
	s_nop 0
	v_mul_f32_e32 v138, v140, v144
	v_mul_f32_e32 v139, v141, v145
	v_cvt_pk_bf16_f32 v149, v138, v139
	s_and_saveexec_b64 s[4:5], vcc
	s_cbranch_execz .LBB0_1316
	v_mul_u32_u24_e32 v138, s33, v214
	v_lshl_add_u32 v138, v166, 1, v138
	global_store_dwordx4 v138, v[146:149], s[62:63]

; __device__ __forceinline__ unsigned cvt_pk_bf16(float lo, float hi) { unsigned r; asm volatile("v_cvt_pk_bf16_f32 %0, %1, %2" : "=v"(r) : "v"(lo), "v"(hi)); return r; }
; __device__ __forceinline__ f32x2 gelu_pk(f32x2 v) {
;     const f32x2 av = __builtin_elementwise_abs(v), d = av * 0.2316418882f + 1.0f;
;     f32x2 t; t.x = __builtin_amdgcn_rcpf(d.x); t.y = __builtin_amdgcn_rcpf(d.y);
;     f32x2 q = t * 0.5307027145f + (-0.7265760135f); q = q * t + 0.7107068705f; q = q * t + (-0.142248368f); q = q * t + 0.127414796f; q = q * t;
;     const f32x2 s = (v * v) * (-0.72134752044f);
;     f32x2 e; e.x = __builtin_amdgcn_exp2f(s.x); e.y = __builtin_amdgcn_exp2f(s.y);
;     const f32x2 h = 0.5f - q * e;
;     return av * h + v * 0.5f;
;     __device__ __forceinline__ void operator()(f32x4 (&acc)[2][2][4][2], const Unit& u, int wr, int wc, int fr, int fq) const {
;     ...
;             for (int n = 0; n < 2; ++n) {
;                 f32x4 pv = (am == 0) ? pvx[n] : acc[(am - 1 < 0 ? 0 : am - 1) >> 2][0][(am - 1 < 0 ? 0 : am - 1) & 3][n];
;                 f32x4 nv = (am == 7) ? nvx[n] : acc[(am + 1 > 7 ? 7 : am + 1) >> 2][0][(am + 1 > 7 ? 7 : am + 1) & 3][n];
;                 f32x4 v = cbv[n] + w0[n] * pv + w1[n] * acc[ai][0][m][n] + w2[n] * nv;
;                 if (edge) {
;                     asm volatile("" ::: "memory");
;                     const f32x4 z = {0.f, 0.f, 0.f, 0.f}; const f32x4 pz = first ? z : pv, nz = lastt ? z : nv;
;                     v = cbv[n] + w0[n] * pz + w1[n] * acc[ai][0][m][n] + w2[n] * nz; }
;                 const f32x2 g0 = gelu_pk((f32x2){v[0], v[1]}), g1 = gelu_pk((f32x2){v[2], v[3]});
;                 const f32x4 bb = acc[ai][1][m][n];
;                 const unsigned lo = cvt_pk_bf16(g0.x * bb[0], g0.y * bb[1]), hi = cvt_pk_bf16(g1.x * bb[2], g1.y * bb[3]);
;                 if (n == 0) { w.x = lo; w.y = hi; } else { w.z = lo; w.w = hi; }
;             }
;             if (ok) STG(u32x4, G + (size_t)tok * DFF + f0) = w;
.LBB0_1320:
	v_pk_fma_f32 v[126:127], v[126:127], v[86:87], v[90:91]
	v_pk_fma_f32 v[128:129], v[128:129], v[88:89], v[92:93]
	v_pk_fma_f32 v[126:127], v[94:95], v[74:75], v[126:127]
	v_pk_fma_f32 v[128:129], v[96:97], v[76:77], v[128:129]
	v_pk_fma_f32 v[126:127], v[78:79], v[132:133], v[126:127]
	v_pk_fma_f32 v[128:129], v[80:81], v[134:135], v[128:129]
	v_and_b32_e32 v133, 0x7fffffff, v127
	v_and_b32_e32 v132, 0x7fffffff, v126
	v_pk_fma_f32 v[134:135], v[132:133], s[78:79], 1.0 op_sel_hi:[1,0,0]
	v_mov_b64_e32 v[136:137], s[82:83]
	v_rcp_f32_e32 v134, v134
	v_rcp_f32_e32 v135, v135
	v_pk_mul_f32 v[140:141], v[126:127], v[126:127]
	s_mov_b32 s4, 0x9ffe
	v_pk_mul_f32 v[140:141], v[140:141], s[90:91] op_sel_hi:[1,0]
	v_pk_fma_f32 v[138:139], v[134:135], s[80:81], v[136:137] op_sel_hi:[1,0,0]
	v_exp_f32_e32 v140, v140
	v_pk_fma_f32 v[138:139], v[134:135], v[138:139], s[84:85] op_sel_hi:[1,1,0]
	v_exp_f32_e32 v141, v141
	v_pk_fma_f32 v[138:139], v[134:135], v[138:139], s[86:87] op_sel_hi:[1,1,0]
	v_cmp_gt_i32_e32 vcc, s4, v203
	v_pk_fma_f32 v[138:139], v[134:135], v[138:139], s[88:89] op_sel_hi:[1,1,0]
	s_nop 0
	v_pk_mul_f32 v[134:135], v[134:135], v[138:139]
	v_pk_mul_f32 v[138:139], v[128:129], v[128:129]
	v_pk_fma_f32 v[134:135], v[140:141], v[134:135], 0.5 op_sel_hi:[1,1,0] neg_lo:[1,0,0] neg_hi:[1,0,0]
	s_nop 0
	v_pk_mul_f32 v[132:133], v[132:133], v[134:135]
	s_nop 0
	v_pk_fma_f32 v[126:127], v[126:127], 0.5, v[132:133] op_sel_hi:[1,0,1]
	v_and_b32_e32 v133, 0x7fffffff, v129
	v_and_b32_e32 v132, 0x7fffffff, v128
	v_pk_fma_f32 v[134:135], v[132:133], s[78:79], 1.0 op_sel_hi:[1,0,0]
	v_mul_f32_e32 v122, v122, v126
	v_rcp_f32_e32 v134, v134
	v_rcp_f32_e32 v135, v135
	v_mul_f32_e32 v123, v123, v127
	v_pk_fma_f32 v[136:137], v[134:135], s[80:81], v[136:137] op_sel_hi:[1,0,0]
	s_nop 0
	v_pk_fma_f32 v[136:137], v[134:135], v[136:137], s[84:85] op_sel_hi:[1,1,0]
	s_nop 0
	v_pk_fma_f32 v[136:137], v[134:135], v[136:137], s[86:87] op_sel_hi:[1,1,0]
	s_nop 0
	v_pk_fma_f32 v[136:137], v[134:135], v[136:137], s[88:89] op_sel_hi:[1,1,0]
	s_nop 0
	v_pk_mul_f32 v[134:135], v[134:135], v[136:137]
	v_pk_mul_f32 v[136:137], v[138:139], s[90:91] op_sel_hi:[1,0]
	s_nop 0
	v_exp_f32_e32 v136, v136
	v_exp_f32_e32 v137, v137
	s_nop 0
	v_pk_fma_f32 v[134:135], v[136:137], v[134:135], 0.5 op_sel_hi:[1,1,0] neg_lo:[1,0,0] neg_hi:[1,0,0]
	s_nop 0
	v_pk_mul_f32 v[132:133], v[132:133], v[134:135]
	s_nop 0
	v_pk_fma_f32 v[128:129], v[128:129], 0.5, v[132:133] op_sel_hi:[1,0,1]
	v_cvt_pk_bf16_f32 v132, v122, v123
	s_nop 0
	v_mul_f32_e32 v122, v124, v128
	v_mul_f32_e32 v123, v125, v129
	v_cvt_pk_bf16_f32 v133, v122, v123
	s_and_saveexec_b64 s[4:5], vcc
	s_cbranch_execz .LBB0_1322
	v_mul_u32_u24_e32 v122, s33, v208
	v_lshl_add_u32 v122, v166, 1, v122
	global_store_dwordx4 v122, v[130:133], s[62:63]

; __device__ __forceinline__ unsigned cvt_pk_bf16(float lo, float hi) { unsigned r; asm volatile("v_cvt_pk_bf16_f32 %0, %1, %2" : "=v"(r) : "v"(lo), "v"(hi)); return r; }
; __device__ __forceinline__ f32x2 gelu_pk(f32x2 v) {
;     const f32x2 av = __builtin_elementwise_abs(v), d = av * 0.2316418882f + 1.0f;
;     f32x2 t; t.x = __builtin_amdgcn_rcpf(d.x); t.y = __builtin_amdgcn_rcpf(d.y);
;     f32x2 q = t * 0.5307027145f + (-0.7265760135f); q = q * t + 0.7107068705f; q = q * t + (-0.142248368f); q = q * t + 0.127414796f; q = q * t;
;     const f32x2 s = (v * v) * (-0.72134752044f);
;     f32x2 e; e.x = __builtin_amdgcn_exp2f(s.x); e.y = __builtin_amdgcn_exp2f(s.y);
;     const f32x2 h = 0.5f - q * e;
;     return av * h + v * 0.5f;
;     __device__ __forceinline__ void operator()(f32x4 (&acc)[2][2][4][2], const Unit& u, int wr, int wc, int fr, int fq) const {
;     ...
;             for (int n = 0; n < 2; ++n) {
;                 f32x4 pv = (am == 0) ? pvx[n] : acc[(am - 1 < 0 ? 0 : am - 1) >> 2][0][(am - 1 < 0 ? 0 : am - 1) & 3][n];
;                 f32x4 nv = (am == 7) ? nvx[n] : acc[(am + 1 > 7 ? 7 : am + 1) >> 2][0][(am + 1 > 7 ? 7 : am + 1) & 3][n];
;                 f32x4 v = cbv[n] + w0[n] * pv + w1[n] * acc[ai][0][m][n] + w2[n] * nv;
;                 if (edge) {
;                     asm volatile("" ::: "memory");
;                     const f32x4 z = {0.f, 0.f, 0.f, 0.f}; const f32x4 pz = first ? z : pv, nz = lastt ? z : nv;
;                     v = cbv[n] + w0[n] * pz + w1[n] * acc[ai][0][m][n] + w2[n] * nz; }
;                 const f32x2 g0 = gelu_pk((f32x2){v[0], v[1]}), g1 = gelu_pk((f32x2){v[2], v[3]});
;                 const f32x4 bb = acc[ai][1][m][n];
;                 const unsigned lo = cvt_pk_bf16(g0.x * bb[0], g0.y * bb[1]), hi = cvt_pk_bf16(g1.x * bb[2], g1.y * bb[3]);
;                 if (n == 0) { w.x = lo; w.y = hi; } else { w.z = lo; w.w = hi; }
;             }
;             if (ok) STG(u32x4, G + (size_t)tok * DFF + f0) = w;
.LBB0_1326:
	v_pk_fma_f32 v[94:95], v[86:87], v[94:95], v[90:91]
	v_mov_b64_e32 v[120:121], s[82:83]
	v_pk_fma_f32 v[94:95], v[62:63], v[74:75], v[94:95]
	v_pk_fma_f32 v[96:97], v[88:89], v[96:97], v[92:93]
	v_pk_fma_f32 v[94:95], v[46:47], v[78:79], v[94:95]
	v_pk_fma_f32 v[96:97], v[64:65], v[76:77], v[96:97]
	v_and_b32_e32 v117, 0x7fffffff, v95
	v_and_b32_e32 v116, 0x7fffffff, v94
	v_pk_fma_f32 v[118:119], v[116:117], s[78:79], 1.0 op_sel_hi:[1,0,0]
	v_pk_mul_f32 v[124:125], v[94:95], v[94:95]
	v_rcp_f32_e32 v118, v118
	v_rcp_f32_e32 v119, v119
	v_pk_mul_f32 v[124:125], v[124:125], s[90:91] op_sel_hi:[1,0]
	v_pk_fma_f32 v[96:97], v[48:49], v[80:81], v[96:97]
	v_exp_f32_e32 v124, v124
	v_pk_fma_f32 v[122:123], v[118:119], s[80:81], v[120:121] op_sel_hi:[1,0,0]
	v_exp_f32_e32 v125, v125
	v_pk_fma_f32 v[122:123], v[118:119], v[122:123], s[84:85] op_sel_hi:[1,1,0]
	s_mov_b32 s4, 0x9ffd
	v_pk_fma_f32 v[122:123], v[118:119], v[122:123], s[86:87] op_sel_hi:[1,1,0]
	v_cmp_gt_i32_e32 vcc, s4, v203
	v_pk_fma_f32 v[122:123], v[118:119], v[122:123], s[88:89] op_sel_hi:[1,1,0]
	s_nop 0
	v_pk_mul_f32 v[118:119], v[118:119], v[122:123]
	v_pk_mul_f32 v[122:123], v[96:97], v[96:97]
	v_pk_fma_f32 v[118:119], v[124:125], v[118:119], 0.5 op_sel_hi:[1,1,0] neg_lo:[1,0,0] neg_hi:[1,0,0]
	s_nop 0
	v_pk_mul_f32 v[116:117], v[116:117], v[118:119]
	s_nop 0
	v_pk_fma_f32 v[94:95], v[94:95], 0.5, v[116:117] op_sel_hi:[1,0,1]
	v_and_b32_e32 v117, 0x7fffffff, v97
	v_and_b32_e32 v116, 0x7fffffff, v96
	v_pk_fma_f32 v[118:119], v[116:117], s[78:79], 1.0 op_sel_hi:[1,0,0]
	v_mul_f32_e32 v82, v82, v94
	v_rcp_f32_e32 v118, v118
	v_rcp_f32_e32 v119, v119
	v_mul_f32_e32 v83, v83, v95
	v_pk_fma_f32 v[120:121], v[118:119], s[80:81], v[120:121] op_sel_hi:[1,0,0]
	s_nop 0
	v_pk_fma_f32 v[120:121], v[118:119], v[120:121], s[84:85] op_sel_hi:[1,1,0]
	s_nop 0
	v_pk_fma_f32 v[120:121], v[118:119], v[120:121], s[86:87] op_sel_hi:[1,1,0]
	s_nop 0
	v_pk_fma_f32 v[120:121], v[118:119], v[120:121], s[88:89] op_sel_hi:[1,1,0]
	s_nop 0
	v_pk_mul_f32 v[118:119], v[118:119], v[120:121]
	v_pk_mul_f32 v[120:121], v[122:123], s[90:91] op_sel_hi:[1,0]
	s_nop 0
	v_exp_f32_e32 v120, v120
	v_exp_f32_e32 v121, v121
	s_nop 0
	v_pk_fma_f32 v[118:119], v[120:121], v[118:119], 0.5 op_sel_hi:[1,1,0] neg_lo:[1,0,0] neg_hi:[1,0,0]
	s_nop 0
	v_pk_mul_f32 v[116:117], v[116:117], v[118:119]
	s_nop 0
	v_pk_fma_f32 v[96:97], v[96:97], 0.5, v[116:117] op_sel_hi:[1,0,1]
	v_cvt_pk_bf16_f32 v116, v82, v83
	s_nop 0
	v_mul_f32_e32 v82, v84, v96
	v_mul_f32_e32 v83, v85, v97
	v_cvt_pk_bf16_f32 v117, v82, v83
	s_and_saveexec_b64 s[4:5], vcc
	s_cbranch_execz .LBB0_1328
	v_mul_u32_u24_e32 v82, s33, v207
	v_lshl_add_u32 v82, v166, 1, v82
	global_store_dwordx4 v82, v[114:117], s[62:63]

; __device__ __forceinline__ unsigned cvt_pk_bf16(float lo, float hi) { unsigned r; asm volatile("v_cvt_pk_bf16_f32 %0, %1, %2" : "=v"(r) : "v"(lo), "v"(hi)); return r; }
; __device__ __forceinline__ f32x2 gelu_pk(f32x2 v) {
;     const f32x2 av = __builtin_elementwise_abs(v), d = av * 0.2316418882f + 1.0f;
;     f32x2 t; t.x = __builtin_amdgcn_rcpf(d.x); t.y = __builtin_amdgcn_rcpf(d.y);
;     f32x2 q = t * 0.5307027145f + (-0.7265760135f); q = q * t + 0.7107068705f; q = q * t + (-0.142248368f); q = q * t + 0.127414796f; q = q * t;
;     const f32x2 s = (v * v) * (-0.72134752044f);
;     f32x2 e; e.x = __builtin_amdgcn_exp2f(s.x); e.y = __builtin_amdgcn_exp2f(s.y);
;     const f32x2 h = 0.5f - q * e;
;     return av * h + v * 0.5f;
;     __device__ __forceinline__ void operator()(f32x4 (&acc)[2][2][4][2], const Unit& u, int wr, int wc, int fr, int fq) const {
;     ...
;             for (int n = 0; n < 2; ++n) {
;                 f32x4 pv = (am == 0) ? pvx[n] : acc[(am - 1 < 0 ? 0 : am - 1) >> 2][0][(am - 1 < 0 ? 0 : am - 1) & 3][n];
;                 f32x4 nv = (am == 7) ? nvx[n] : acc[(am + 1 > 7 ? 7 : am + 1) >> 2][0][(am + 1 > 7 ? 7 : am + 1) & 3][n];
;                 f32x4 v = cbv[n] + w0[n] * pv + w1[n] * acc[ai][0][m][n] + w2[n] * nv;
;                 if (edge) {
;                     asm volatile("" ::: "memory");
;                     const f32x4 z = {0.f, 0.f, 0.f, 0.f}; const f32x4 pz = first ? z : pv, nz = lastt ? z : nv;
;                     v = cbv[n] + w0[n] * pz + w1[n] * acc[ai][0][m][n] + w2[n] * nz; }
;                 const f32x2 g0 = gelu_pk((f32x2){v[0], v[1]}), g1 = gelu_pk((f32x2){v[2], v[3]});
;                 const f32x4 bb = acc[ai][1][m][n];
;                 const unsigned lo = cvt_pk_bf16(g0.x * bb[0], g0.y * bb[1]), hi = cvt_pk_bf16(g1.x * bb[2], g1.y * bb[3]);
;                 if (n == 0) { w.x = lo; w.y = hi; } else { w.z = lo; w.w = hi; }
;             }
;             if (ok) STG(u32x4, G + (size_t)tok * DFF + f0) = w;
.LBB0_1332:
	v_pk_fma_f32 v[62:63], v[62:63], v[86:87], v[90:91]
	v_pk_fma_f32 v[64:65], v[64:65], v[88:89], v[92:93]
	v_pk_fma_f32 v[62:63], v[46:47], v[74:75], v[62:63]
	v_pk_fma_f32 v[64:65], v[48:49], v[76:77], v[64:65]
	v_pk_fma_f32 v[62:63], v[78:79], v[68:69], v[62:63]
	v_pk_fma_f32 v[64:65], v[80:81], v[70:71], v[64:65]
	v_and_b32_e32 v69, 0x7fffffff, v63
	v_and_b32_e32 v68, 0x7fffffff, v62
	v_pk_fma_f32 v[70:71], v[68:69], s[78:79], 1.0 op_sel_hi:[1,0,0]
	v_mov_b64_e32 v[72:73], s[82:83]
	v_rcp_f32_e32 v70, v70
	v_rcp_f32_e32 v71, v71
	v_pk_mul_f32 v[84:85], v[62:63], v[62:63]
	s_mov_b32 s4, 0x9ffc
	v_pk_mul_f32 v[84:85], v[84:85], s[90:91] op_sel_hi:[1,0]
	v_pk_fma_f32 v[82:83], v[70:71], s[80:81], v[72:73] op_sel_hi:[1,0,0]
	v_exp_f32_e32 v84, v84
	v_pk_fma_f32 v[82:83], v[70:71], v[82:83], s[84:85] op_sel_hi:[1,1,0]
	v_exp_f32_e32 v85, v85
	v_pk_fma_f32 v[82:83], v[70:71], v[82:83], s[86:87] op_sel_hi:[1,1,0]
	v_cmp_gt_i32_e32 vcc, s4, v203
	v_pk_fma_f32 v[82:83], v[70:71], v[82:83], s[88:89] op_sel_hi:[1,1,0]
	s_nop 0
	v_pk_mul_f32 v[70:71], v[70:71], v[82:83]
	v_pk_mul_f32 v[82:83], v[64:65], v[64:65]
	v_pk_fma_f32 v[70:71], v[84:85], v[70:71], 0.5 op_sel_hi:[1,1,0] neg_lo:[1,0,0] neg_hi:[1,0,0]
	s_nop 0
	v_pk_mul_f32 v[68:69], v[68:69], v[70:71]
	s_nop 0
	v_pk_fma_f32 v[62:63], v[62:63], 0.5, v[68:69] op_sel_hi:[1,0,1]
	v_and_b32_e32 v69, 0x7fffffff, v65
	v_and_b32_e32 v68, 0x7fffffff, v64
	v_pk_fma_f32 v[70:71], v[68:69], s[78:79], 1.0 op_sel_hi:[1,0,0]
	v_mul_f32_e32 v58, v58, v62
	v_rcp_f32_e32 v70, v70
	v_rcp_f32_e32 v71, v71
	v_mul_f32_e32 v59, v59, v63
	v_pk_fma_f32 v[72:73], v[70:71], s[80:81], v[72:73] op_sel_hi:[1,0,0]
	s_nop 0
	v_pk_fma_f32 v[72:73], v[70:71], v[72:73], s[84:85] op_sel_hi:[1,1,0]
	s_nop 0
	v_pk_fma_f32 v[72:73], v[70:71], v[72:73], s[86:87] op_sel_hi:[1,1,0]
	s_nop 0
	v_pk_fma_f32 v[72:73], v[70:71], v[72:73], s[88:89] op_sel_hi:[1,1,0]
	s_nop 0
	v_pk_mul_f32 v[70:71], v[70:71], v[72:73]
	v_pk_mul_f32 v[72:73], v[82:83], s[90:91] op_sel_hi:[1,0]
	s_nop 0
	v_exp_f32_e32 v72, v72
	v_exp_f32_e32 v73, v73
	s_nop 0
	v_pk_fma_f32 v[70:71], v[72:73], v[70:71], 0.5 op_sel_hi:[1,1,0] neg_lo:[1,0,0] neg_hi:[1,0,0]
	s_nop 0
	v_pk_mul_f32 v[68:69], v[68:69], v[70:71]
	s_nop 0
	v_pk_fma_f32 v[64:65], v[64:65], 0.5, v[68:69] op_sel_hi:[1,0,1]
	v_cvt_pk_bf16_f32 v68, v58, v59
	s_nop 0
	v_mul_f32_e32 v58, v60, v64
	v_mul_f32_e32 v59, v61, v65
	v_cvt_pk_bf16_f32 v69, v58, v59
	s_and_saveexec_b64 s[4:5], vcc
	s_cbranch_execz .LBB0_1334
	v_mul_u32_u24_e32 v58, s33, v206
	v_lshl_add_u32 v58, v166, 1, v58
	global_store_dwordx4 v58, v[66:69], s[62:63]

; __device__ __forceinline__ unsigned cvt_pk_bf16(float lo, float hi) { unsigned r; asm volatile("v_cvt_pk_bf16_f32 %0, %1, %2" : "=v"(r) : "v"(lo), "v"(hi)); return r; }
; __device__ __forceinline__ f32x2 gelu_pk(f32x2 v) {
;     const f32x2 av = __builtin_elementwise_abs(v), d = av * 0.2316418882f + 1.0f;
;     f32x2 t; t.x = __builtin_amdgcn_rcpf(d.x); t.y = __builtin_amdgcn_rcpf(d.y);
;     f32x2 q = t * 0.5307027145f + (-0.7265760135f); q = q * t + 0.7107068705f; q = q * t + (-0.142248368f); q = q * t + 0.127414796f; q = q * t;
;     const f32x2 s = (v * v) * (-0.72134752044f);
;     f32x2 e; e.x = __builtin_amdgcn_exp2f(s.x); e.y = __builtin_amdgcn_exp2f(s.y);
;     const f32x2 h = 0.5f - q * e;
;     return av * h + v * 0.5f;
;     __device__ __forceinline__ void operator()(f32x4 (&acc)[2][2][4][2], const Unit& u, int wr, int wc, int fr, int fq) const {
;     ...
;             for (int n = 0; n < 2; ++n) {
;                 f32x4 pv = (am == 0) ? pvx[n] : acc[(am - 1 < 0 ? 0 : am - 1) >> 2][0][(am - 1 < 0 ? 0 : am - 1) & 3][n];
;                 f32x4 nv = (am == 7) ? nvx[n] : acc[(am + 1 > 7 ? 7 : am + 1) >> 2][0][(am + 1 > 7 ? 7 : am + 1) & 3][n];
;                 f32x4 v = cbv[n] + w0[n] * pv + w1[n] * acc[ai][0][m][n] + w2[n] * nv;
;                 if (edge) {
;                     asm volatile("" ::: "memory");
;                     const f32x4 z = {0.f, 0.f, 0.f, 0.f}; const f32x4 pz = first ? z : pv, nz = lastt ? z : nv;
;                     v = cbv[n] + w0[n] * pz + w1[n] * acc[ai][0][m][n] + w2[n] * nz; }
;                 const f32x2 g0 = gelu_pk((f32x2){v[0], v[1]}), g1 = gelu_pk((f32x2){v[2], v[3]});
;                 const f32x4 bb = acc[ai][1][m][n];
;                 const unsigned lo = cvt_pk_bf16(g0.x * bb[0], g0.y * bb[1]), hi = cvt_pk_bf16(g1.x * bb[2], g1.y * bb[3]);
;                 if (n == 0) { w.x = lo; w.y = hi; } else { w.z = lo; w.w = hi; }
;             }
;             if (ok) STG(u32x4, G + (size_t)tok * DFF + f0) = w;
.LBB0_1338:
	v_pk_fma_f32 v[46:47], v[86:87], v[46:47], v[90:91]
	v_mov_b64_e32 v[56:57], s[82:83]
	v_pk_fma_f32 v[46:47], v[30:31], v[74:75], v[46:47]
	v_pk_fma_f32 v[48:49], v[88:89], v[48:49], v[92:93]
	v_pk_fma_f32 v[46:47], v[6:7], v[78:79], v[46:47]
	v_pk_fma_f32 v[48:49], v[32:33], v[76:77], v[48:49]
	v_and_b32_e32 v53, 0x7fffffff, v47
	v_and_b32_e32 v52, 0x7fffffff, v46
	v_pk_fma_f32 v[54:55], v[52:53], s[78:79], 1.0 op_sel_hi:[1,0,0]
	v_pk_mul_f32 v[60:61], v[46:47], v[46:47]
	v_rcp_f32_e32 v54, v54
	v_rcp_f32_e32 v55, v55
	v_pk_mul_f32 v[60:61], v[60:61], s[90:91] op_sel_hi:[1,0]
	v_pk_fma_f32 v[48:49], v[8:9], v[80:81], v[48:49]
	v_exp_f32_e32 v60, v60
	v_pk_fma_f32 v[58:59], v[54:55], s[80:81], v[56:57] op_sel_hi:[1,0,0]
	v_exp_f32_e32 v61, v61
	v_pk_fma_f32 v[58:59], v[54:55], v[58:59], s[84:85] op_sel_hi:[1,1,0]
	s_mov_b32 s4, 0x9ffb
	v_pk_fma_f32 v[58:59], v[54:55], v[58:59], s[86:87] op_sel_hi:[1,1,0]
	v_cmp_gt_i32_e32 vcc, s4, v203
	v_pk_fma_f32 v[58:59], v[54:55], v[58:59], s[88:89] op_sel_hi:[1,1,0]
	s_nop 0
	v_pk_mul_f32 v[54:55], v[54:55], v[58:59]
	v_pk_mul_f32 v[58:59], v[48:49], v[48:49]
	v_pk_fma_f32 v[54:55], v[60:61], v[54:55], 0.5 op_sel_hi:[1,1,0] neg_lo:[1,0,0] neg_hi:[1,0,0]
	s_nop 0
	v_pk_mul_f32 v[52:53], v[52:53], v[54:55]
	s_nop 0
	v_pk_fma_f32 v[46:47], v[46:47], 0.5, v[52:53] op_sel_hi:[1,0,1]
	v_and_b32_e32 v53, 0x7fffffff, v49
	v_and_b32_e32 v52, 0x7fffffff, v48
	v_pk_fma_f32 v[54:55], v[52:53], s[78:79], 1.0 op_sel_hi:[1,0,0]
	v_mul_f32_e32 v42, v42, v46
	v_rcp_f32_e32 v54, v54
	v_rcp_f32_e32 v55, v55
	v_mul_f32_e32 v43, v43, v47
	v_pk_fma_f32 v[56:57], v[54:55], s[80:81], v[56:57] op_sel_hi:[1,0,0]
	s_nop 0
	v_pk_fma_f32 v[56:57], v[54:55], v[56:57], s[84:85] op_sel_hi:[1,1,0]
	s_nop 0
	v_pk_fma_f32 v[56:57], v[54:55], v[56:57], s[86:87] op_sel_hi:[1,1,0]
	s_nop 0
	v_pk_fma_f32 v[56:57], v[54:55], v[56:57], s[88:89] op_sel_hi:[1,1,0]
	s_nop 0
	v_pk_mul_f32 v[54:55], v[54:55], v[56:57]
	v_pk_mul_f32 v[56:57], v[58:59], s[90:91] op_sel_hi:[1,0]
	s_nop 0
	v_exp_f32_e32 v56, v56
	v_exp_f32_e32 v57, v57
	s_nop 0
	v_pk_fma_f32 v[54:55], v[56:57], v[54:55], 0.5 op_sel_hi:[1,1,0] neg_lo:[1,0,0] neg_hi:[1,0,0]
	s_nop 0
	v_pk_mul_f32 v[52:53], v[52:53], v[54:55]
	s_nop 0
	v_pk_fma_f32 v[48:49], v[48:49], 0.5, v[52:53] op_sel_hi:[1,0,1]
	v_cvt_pk_bf16_f32 v52, v42, v43
	s_nop 0
	v_mul_f32_e32 v42, v44, v48
	v_mul_f32_e32 v43, v45, v49
	v_cvt_pk_bf16_f32 v53, v42, v43
	s_and_saveexec_b64 s[4:5], vcc
	s_cbranch_execz .LBB0_1340
	v_mul_u32_u24_e32 v42, s33, v205
	v_lshl_add_u32 v42, v166, 1, v42
	global_store_dwordx4 v42, v[50:53], s[62:63]

; __device__ __forceinline__ unsigned cvt_pk_bf16(float lo, float hi) { unsigned r; asm volatile("v_cvt_pk_bf16_f32 %0, %1, %2" : "=v"(r) : "v"(lo), "v"(hi)); return r; }
; __device__ __forceinline__ f32x2 gelu_pk(f32x2 v) {
;     const f32x2 av = __builtin_elementwise_abs(v), d = av * 0.2316418882f + 1.0f;
;     f32x2 t; t.x = __builtin_amdgcn_rcpf(d.x); t.y = __builtin_amdgcn_rcpf(d.y);
;     f32x2 q = t * 0.5307027145f + (-0.7265760135f); q = q * t + 0.7107068705f; q = q * t + (-0.142248368f); q = q * t + 0.127414796f; q = q * t;
;     const f32x2 s = (v * v) * (-0.72134752044f);
;     f32x2 e; e.x = __builtin_amdgcn_exp2f(s.x); e.y = __builtin_amdgcn_exp2f(s.y);
;     const f32x2 h = 0.5f - q * e;
;     return av * h + v * 0.5f;
;     __device__ __forceinline__ void operator()(f32x4 (&acc)[2][2][4][2], const Unit& u, int wr, int wc, int fr, int fq) const {
;     ...
;             for (int n = 0; n < 2; ++n) {
;                 f32x4 pv = (am == 0) ? pvx[n] : acc[(am - 1 < 0 ? 0 : am - 1) >> 2][0][(am - 1 < 0 ? 0 : am - 1) & 3][n];
;                 f32x4 nv = (am == 7) ? nvx[n] : acc[(am + 1 > 7 ? 7 : am + 1) >> 2][0][(am + 1 > 7 ? 7 : am + 1) & 3][n];
;                 f32x4 v = cbv[n] + w0[n] * pv + w1[n] * acc[ai][0][m][n] + w2[n] * nv;
;                 if (edge) {
;                     asm volatile("" ::: "memory");
;                     const f32x4 z = {0.f, 0.f, 0.f, 0.f}; const f32x4 pz = first ? z : pv, nz = lastt ? z : nv;
;                     v = cbv[n] + w0[n] * pz + w1[n] * acc[ai][0][m][n] + w2[n] * nz; }
;                 const f32x2 g0 = gelu_pk((f32x2){v[0], v[1]}), g1 = gelu_pk((f32x2){v[2], v[3]});
;                 const f32x4 bb = acc[ai][1][m][n];
;                 const unsigned lo = cvt_pk_bf16(g0.x * bb[0], g0.y * bb[1]), hi = cvt_pk_bf16(g1.x * bb[2], g1.y * bb[3]);
;                 if (n == 0) { w.x = lo; w.y = hi; } else { w.z = lo; w.w = hi; }
;             }
;             if (ok) STG(u32x4, G + (size_t)tok * DFF + f0) = w;
.LBB0_1344:
	v_pk_fma_f32 v[30:31], v[30:31], v[86:87], v[90:91]
	v_pk_fma_f32 v[32:33], v[32:33], v[88:89], v[92:93]
	v_pk_fma_f32 v[30:31], v[6:7], v[74:75], v[30:31]
	v_pk_fma_f32 v[32:33], v[8:9], v[76:77], v[32:33]
	v_pk_fma_f32 v[30:31], v[78:79], v[36:37], v[30:31]
	v_pk_fma_f32 v[32:33], v[80:81], v[38:39], v[32:33]
	v_and_b32_e32 v37, 0x7fffffff, v31
	v_and_b32_e32 v36, 0x7fffffff, v30
	v_pk_fma_f32 v[38:39], v[36:37], s[78:79], 1.0 op_sel_hi:[1,0,0]
	v_mov_b64_e32 v[40:41], s[82:83]
	v_rcp_f32_e32 v38, v38
	v_rcp_f32_e32 v39, v39
	v_pk_mul_f32 v[44:45], v[30:31], v[30:31]
	s_mov_b32 s4, 0x9ffa
	v_pk_mul_f32 v[44:45], v[44:45], s[90:91] op_sel_hi:[1,0]
	v_pk_fma_f32 v[42:43], v[38:39], s[80:81], v[40:41] op_sel_hi:[1,0,0]
	v_exp_f32_e32 v44, v44
	v_pk_fma_f32 v[42:43], v[38:39], v[42:43], s[84:85] op_sel_hi:[1,1,0]
	v_exp_f32_e32 v45, v45
	v_pk_fma_f32 v[42:43], v[38:39], v[42:43], s[86:87] op_sel_hi:[1,1,0]
	v_cmp_gt_i32_e32 vcc, s4, v203
	v_pk_fma_f32 v[42:43], v[38:39], v[42:43], s[88:89] op_sel_hi:[1,1,0]
	s_nop 0
	v_pk_mul_f32 v[38:39], v[38:39], v[42:43]
	v_pk_mul_f32 v[42:43], v[32:33], v[32:33]
	v_pk_fma_f32 v[38:39], v[44:45], v[38:39], 0.5 op_sel_hi:[1,1,0] neg_lo:[1,0,0] neg_hi:[1,0,0]
	s_nop 0
	v_pk_mul_f32 v[36:37], v[36:37], v[38:39]
	s_nop 0
	v_pk_fma_f32 v[30:31], v[30:31], 0.5, v[36:37] op_sel_hi:[1,0,1]
	v_and_b32_e32 v37, 0x7fffffff, v33
	v_and_b32_e32 v36, 0x7fffffff, v32
	v_pk_fma_f32 v[38:39], v[36:37], s[78:79], 1.0 op_sel_hi:[1,0,0]
	v_mul_f32_e32 v26, v26, v30
	v_rcp_f32_e32 v38, v38
	v_rcp_f32_e32 v39, v39
	v_mul_f32_e32 v27, v27, v31
	v_pk_fma_f32 v[40:41], v[38:39], s[80:81], v[40:41] op_sel_hi:[1,0,0]
	s_nop 0
	v_pk_fma_f32 v[40:41], v[38:39], v[40:41], s[84:85] op_sel_hi:[1,1,0]
	s_nop 0
	v_pk_fma_f32 v[40:41], v[38:39], v[40:41], s[86:87] op_sel_hi:[1,1,0]
	s_nop 0
	v_pk_fma_f32 v[40:41], v[38:39], v[40:41], s[88:89] op_sel_hi:[1,1,0]
	s_nop 0
	v_pk_mul_f32 v[38:39], v[38:39], v[40:41]
	v_pk_mul_f32 v[40:41], v[42:43], s[90:91] op_sel_hi:[1,0]
	s_nop 0
	v_exp_f32_e32 v40, v40
	v_exp_f32_e32 v41, v41
	s_nop 0
	v_pk_fma_f32 v[38:39], v[40:41], v[38:39], 0.5 op_sel_hi:[1,1,0] neg_lo:[1,0,0] neg_hi:[1,0,0]
	s_nop 0
	v_pk_mul_f32 v[36:37], v[36:37], v[38:39]
	s_nop 0
	v_pk_fma_f32 v[32:33], v[32:33], 0.5, v[36:37] op_sel_hi:[1,0,1]
	v_cvt_pk_bf16_f32 v36, v26, v27
	s_nop 0
	v_mul_f32_e32 v26, v28, v32
	v_mul_f32_e32 v27, v29, v33
	v_cvt_pk_bf16_f32 v37, v26, v27
	s_and_saveexec_b64 s[4:5], vcc
	s_cbranch_execz .LBB0_1346
	v_mul_u32_u24_e32 v26, s33, v204
	v_lshl_add_u32 v26, v166, 1, v26
	global_store_dwordx4 v26, v[34:37], s[62:63]

; __device__ __forceinline__ unsigned cvt_pk_bf16(float lo, float hi) { unsigned r; asm volatile("v_cvt_pk_bf16_f32 %0, %1, %2" : "=v"(r) : "v"(lo), "v"(hi)); return r; }
; __device__ __forceinline__ f32x2 gelu_pk(f32x2 v) {
;     const f32x2 av = __builtin_elementwise_abs(v), d = av * 0.2316418882f + 1.0f;
;     f32x2 t; t.x = __builtin_amdgcn_rcpf(d.x); t.y = __builtin_amdgcn_rcpf(d.y);
;     f32x2 q = t * 0.5307027145f + (-0.7265760135f); q = q * t + 0.7107068705f; q = q * t + (-0.142248368f); q = q * t + 0.127414796f; q = q * t;
;     const f32x2 s = (v * v) * (-0.72134752044f);
;     f32x2 e; e.x = __builtin_amdgcn_exp2f(s.x); e.y = __builtin_amdgcn_exp2f(s.y);
;     const f32x2 h = 0.5f - q * e;
;     return av * h + v * 0.5f;
;     __device__ __forceinline__ void operator()(f32x4 (&acc)[2][2][4][2], const Unit& u, int wr, int wc, int fr, int fq) const {
;     ...
;             for (int n = 0; n < 2; ++n) {
;                 f32x4 pv = (am == 0) ? pvx[n] : acc[(am - 1 < 0 ? 0 : am - 1) >> 2][0][(am - 1 < 0 ? 0 : am - 1) & 3][n];
;                 f32x4 nv = (am == 7) ? nvx[n] : acc[(am + 1 > 7 ? 7 : am + 1) >> 2][0][(am + 1 > 7 ? 7 : am + 1) & 3][n];
;                 f32x4 v = cbv[n] + w0[n] * pv + w1[n] * acc[ai][0][m][n] + w2[n] * nv;
;                 if (edge) {
;                     asm volatile("" ::: "memory");
;                     const f32x4 z = {0.f, 0.f, 0.f, 0.f}; const f32x4 pz = first ? z : pv, nz = lastt ? z : nv;
;                     v = cbv[n] + w0[n] * pz + w1[n] * acc[ai][0][m][n] + w2[n] * nz; }
;                 const f32x2 g0 = gelu_pk((f32x2){v[0], v[1]}), g1 = gelu_pk((f32x2){v[2], v[3]});
;                 const f32x4 bb = acc[ai][1][m][n];
;                 const unsigned lo = cvt_pk_bf16(g0.x * bb[0], g0.y * bb[1]), hi = cvt_pk_bf16(g1.x * bb[2], g1.y * bb[3]);
;                 if (n == 0) { w.x = lo; w.y = hi; } else { w.z = lo; w.w = hi; }
;             }
;             if (ok) STG(u32x4, G + (size_t)tok * DFF + f0) = w;
.LBB0_1350:
	v_pk_fma_f32 v[6:7], v[86:87], v[6:7], v[90:91]
	v_pk_fma_f32 v[8:9], v[88:89], v[8:9], v[92:93]
	v_pk_fma_f32 v[6:7], v[10:11], v[74:75], v[6:7]
	v_pk_fma_f32 v[8:9], v[12:13], v[76:77], v[8:9]
	v_pk_fma_f32 v[6:7], v[78:79], v[170:171], v[6:7]
	v_mov_b64_e32 v[12:13], s[82:83]
	v_and_b32_e32 v11, 0x7fffffff, v7
	v_and_b32_e32 v10, 0x7fffffff, v6
	v_pk_fma_f32 v[16:17], v[10:11], s[78:79], 1.0 op_sel_hi:[1,0,0]
	v_pk_mul_f32 v[20:21], v[6:7], v[6:7]
	v_rcp_f32_e32 v16, v16
	v_rcp_f32_e32 v17, v17
	s_waitcnt lgkmcnt(0)
	v_pk_fma_f32 v[8:9], v[80:81], v[168:169], v[8:9]
	v_pk_mul_f32 v[20:21], v[20:21], s[90:91] op_sel_hi:[1,0]
	v_and_b32_e32 v23, 0x7fffffff, v9
	v_pk_fma_f32 v[18:19], v[16:17], s[80:81], v[12:13] op_sel_hi:[1,0,0]
	v_exp_f32_e32 v20, v20
	v_pk_fma_f32 v[18:19], v[16:17], v[18:19], s[84:85] op_sel_hi:[1,1,0]
	v_exp_f32_e32 v21, v21
	v_and_b32_e32 v22, 0x7fffffff, v8
	v_pk_fma_f32 v[18:19], v[16:17], v[18:19], s[86:87] op_sel_hi:[1,1,0]
	v_pk_fma_f32 v[24:25], v[22:23], s[78:79], 1.0 op_sel_hi:[1,0,0]
	v_pk_fma_f32 v[18:19], v[16:17], v[18:19], s[88:89] op_sel_hi:[1,1,0]
	v_rcp_f32_e32 v24, v24
	v_rcp_f32_e32 v25, v25
	v_pk_mul_f32 v[16:17], v[16:17], v[18:19]
	v_pk_mul_f32 v[18:19], v[8:9], v[8:9]
	v_pk_fma_f32 v[16:17], v[20:21], v[16:17], 0.5 op_sel_hi:[1,1,0] neg_lo:[1,0,0] neg_hi:[1,0,0]
	s_mov_b32 s4, 0x9ff9
	v_pk_mul_f32 v[10:11], v[10:11], v[16:17]
	v_cmp_gt_i32_e32 vcc, s4, v203
	v_pk_fma_f32 v[6:7], v[6:7], 0.5, v[10:11] op_sel_hi:[1,0,1]
	v_pk_fma_f32 v[10:11], v[24:25], s[80:81], v[12:13] op_sel_hi:[1,0,0]
	v_pk_mul_f32 v[12:13], v[18:19], s[90:91] op_sel_hi:[1,0]
	v_pk_fma_f32 v[10:11], v[24:25], v[10:11], s[84:85] op_sel_hi:[1,1,0]
	v_exp_f32_e32 v12, v12
	v_exp_f32_e32 v13, v13
	v_pk_fma_f32 v[10:11], v[24:25], v[10:11], s[86:87] op_sel_hi:[1,1,0]
	v_mul_f32_e32 v2, v2, v6
	v_pk_fma_f32 v[10:11], v[24:25], v[10:11], s[88:89] op_sel_hi:[1,1,0]
	v_mul_f32_e32 v3, v3, v7
	v_pk_mul_f32 v[10:11], v[24:25], v[10:11]
	s_and_b64 s[6:7], s[38:39], vcc
	v_pk_fma_f32 v[10:11], v[12:13], v[10:11], 0.5 op_sel_hi:[1,1,0] neg_lo:[1,0,0] neg_hi:[1,0,0]
	v_cvt_pk_bf16_f32 v16, v2, v3
	s_nop 0
	v_pk_mul_f32 v[10:11], v[22:23], v[10:11]
	s_nop 0
	v_pk_fma_f32 v[8:9], v[8:9], 0.5, v[10:11] op_sel_hi:[1,0,1]
	s_nop 0
	v_mul_f32_e32 v2, v4, v8
	v_mul_f32_e32 v3, v5, v9
	v_cvt_pk_bf16_f32 v17, v2, v3
	s_and_saveexec_b64 s[4:5], s[6:7]
	s_cbranch_execz .LBB0_1352
	v_mul_u32_u24_e32 v2, s33, v202
	v_lshl_add_u32 v2, v166, 1, v2
	global_store_dwordx4 v2, v[14:17], s[62:63]
